# 4-phase K-loops (P4/P5/P6) + tail-start vmcnt(6) guard for the last staged A-half-1 buffer
# baseline (speedup 1.0000x reference)
.LBB0_95:
	v_add_u32_e32 v156, 0x10000, v143
	ds_read_b128 v[144:147], v156
	ds_read_b128 v[148:151], v156 offset:1024
	ds_read_b128 v[152:155], v156 offset:2048
	ds_read_b128 v[156:159], v156 offset:3072
	ds_read_b128 v[160:163], v142
	ds_read_b128 v[164:167], v142 offset:1024
	ds_read_b128 v[168:171], v142 offset:2048
	ds_read_b128 v[172:175], v142 offset:3072
	ds_read_b128 v[176:179], v142 offset:4096
	ds_read_b128 v[180:183], v142 offset:5120
	ds_read_b128 v[184:187], v142 offset:6144
	ds_read_b128 v[188:191], v142 offset:7168
	s_add_i32 s41, 0, 0x10000
	v_lshl_add_u64 v[210:211], v[138:139], 0, s[14:15]
	s_add_i32 s40, s43, 0xc000
	v_lshl_add_u64 v[192:193], v[210:211], 0, s[44:45]
	s_mov_b32 m0, s40
	v_lshl_add_u64 v[212:213], v[140:141], 0, s[14:15]
	s_add_i32 s37, s43, 0xe000
	global_load_lds_dwordx4 v[192:193], off
	v_lshl_add_u64 v[192:193], v[212:213], 0, s[44:45]
	s_mov_b32 m0, s37
	s_nop 0
	global_load_lds_dwordx4 v[192:193], off
	v_add_u32_e32 v197, 0x14000, v143
	ds_read_b128 v[192:195], v197
	ds_read_b128 v[198:201], v197 offset:1024
	ds_read_b128 v[202:205], v197 offset:2048
	ds_read_b128 v[206:209], v197 offset:3072
	s_waitcnt vmcnt(8)
	s_waitcnt lgkmcnt(0)
	s_barrier
	s_setprio 1
	v_mfma_f32_16x16x32_bf16 v[126:129], v[144:147], v[160:163], v[126:129]
	v_mfma_f32_16x16x32_bf16 v[122:125], v[152:155], v[160:163], v[122:125]
	v_mfma_f32_16x16x32_bf16 v[118:121], v[144:147], v[168:171], v[118:121]
	v_mfma_f32_16x16x32_bf16 v[114:117], v[152:155], v[168:171], v[114:117]
	v_mfma_f32_16x16x32_bf16 v[110:113], v[144:147], v[176:179], v[110:113]
	v_mfma_f32_16x16x32_bf16 v[106:109], v[152:155], v[176:179], v[106:109]
	v_mfma_f32_16x16x32_bf16 v[102:105], v[144:147], v[184:187], v[102:105]
	v_mfma_f32_16x16x32_bf16 v[98:101], v[152:155], v[184:187], v[98:101]
	v_mfma_f32_16x16x32_bf16 v[126:129], v[148:151], v[164:167], v[126:129]
	v_mfma_f32_16x16x32_bf16 v[122:125], v[156:159], v[164:167], v[122:125]
	v_mfma_f32_16x16x32_bf16 v[118:121], v[148:151], v[172:175], v[118:121]
	v_mfma_f32_16x16x32_bf16 v[114:117], v[156:159], v[172:175], v[114:117]
	v_mfma_f32_16x16x32_bf16 v[110:113], v[148:151], v[180:183], v[110:113]
	v_mfma_f32_16x16x32_bf16 v[106:109], v[156:159], v[180:183], v[106:109]
	v_mfma_f32_16x16x32_bf16 v[102:105], v[148:151], v[188:191], v[102:105]
	v_mfma_f32_16x16x32_bf16 v[98:101], v[156:159], v[188:191], v[98:101]
	v_mfma_f32_16x16x32_bf16 v[94:97], v[192:195], v[160:163], v[94:97]
	v_mfma_f32_16x16x32_bf16 v[90:93], v[202:205], v[160:163], v[90:93]
	v_mfma_f32_16x16x32_bf16 v[86:89], v[192:195], v[168:171], v[86:89]
	v_mfma_f32_16x16x32_bf16 v[82:85], v[202:205], v[168:171], v[82:85]
	v_mfma_f32_16x16x32_bf16 v[78:81], v[192:195], v[176:179], v[78:81]
	v_mfma_f32_16x16x32_bf16 v[70:73], v[202:205], v[176:179], v[70:73]
	v_mfma_f32_16x16x32_bf16 v[66:69], v[192:195], v[184:187], v[66:69]
	v_mfma_f32_16x16x32_bf16 v[62:65], v[202:205], v[184:187], v[62:65]
	v_mfma_f32_16x16x32_bf16 v[94:97], v[198:201], v[164:167], v[94:97]
	v_mfma_f32_16x16x32_bf16 v[90:93], v[206:209], v[164:167], v[90:93]
	v_mfma_f32_16x16x32_bf16 v[86:89], v[198:201], v[172:175], v[86:89]
	v_mfma_f32_16x16x32_bf16 v[82:85], v[206:209], v[172:175], v[82:85]
	v_mfma_f32_16x16x32_bf16 v[78:81], v[198:201], v[180:183], v[78:81]
	v_mfma_f32_16x16x32_bf16 v[70:73], v[206:209], v[180:183], v[70:73]
	v_mfma_f32_16x16x32_bf16 v[66:69], v[198:201], v[188:191], v[66:69]
	v_mfma_f32_16x16x32_bf16 v[62:65], v[206:209], v[188:191], v[62:65]
	s_setprio 0
	s_mov_b32 m0, s43
	v_lshl_add_u64 v[218:219], v[210:211], 0, s[82:83]
	s_barrier
	ds_read_b128 v[160:163], v142 offset:16384
	ds_read_b128 v[164:167], v142 offset:17408
	ds_read_b128 v[168:171], v142 offset:18432
	ds_read_b128 v[172:175], v142 offset:19456
	ds_read_b128 v[176:179], v142 offset:20480
	ds_read_b128 v[180:183], v142 offset:21504
	ds_read_b128 v[184:187], v142 offset:22528
	ds_read_b128 v[188:191], v142 offset:23552
	global_load_lds_dwordx4 v[218:219], off
	v_lshl_add_u64 v[218:219], v[212:213], 0, s[82:83]
	s_mov_b32 m0, s73
	s_nop 0
	global_load_lds_dwordx4 v[218:219], off
	s_add_i32 s70, 0, 0x14000
	v_lshl_add_u64 v[214:215], v[134:135], 0, s[14:15]
	s_add_i32 s41, s41, s42
	v_lshl_add_u64 v[216:217], v[214:215], 0, s[76:77]
	s_mov_b32 m0, s41
	s_nop 0
	global_load_lds_dwordx4 v[216:217], off
	v_lshl_add_u64 v[216:217], v[136:137], 0, s[14:15]
	v_lshl_add_u64 v[218:219], v[216:217], 0, s[76:77]
	s_add_i32 m0, s41, 0x2000
	s_nop 0
	global_load_lds_dwordx4 v[218:219], off
	s_add_i32 s41, s70, s42
	v_lshl_add_u64 v[218:219], v[214:215], 0, s[80:81]
	s_mov_b32 m0, s41
	s_nop 0
	global_load_lds_dwordx4 v[218:219], off
	v_lshl_add_u64 v[218:219], v[216:217], 0, s[80:81]
	s_add_i32 m0, s41, 0x2000
	s_nop 0
	global_load_lds_dwordx4 v[218:219], off
	s_waitcnt vmcnt(8)
	s_waitcnt lgkmcnt(0)
	s_barrier
	s_setprio 1
	v_mfma_f32_16x16x32_bf16 v[58:61], v[144:147], v[160:163], v[58:61]
	v_mfma_f32_16x16x32_bf16 v[54:57], v[152:155], v[160:163], v[54:57]
	v_mfma_f32_16x16x32_bf16 v[50:53], v[144:147], v[168:171], v[50:53]
	v_mfma_f32_16x16x32_bf16 v[46:49], v[152:155], v[168:171], v[46:49]
	v_mfma_f32_16x16x32_bf16 v[42:45], v[144:147], v[176:179], v[42:45]
	v_mfma_f32_16x16x32_bf16 v[38:41], v[152:155], v[176:179], v[38:41]
	v_mfma_f32_16x16x32_bf16 v[34:37], v[144:147], v[184:187], v[34:37]
	v_mfma_f32_16x16x32_bf16 v[30:33], v[152:155], v[184:187], v[30:33]
	v_mfma_f32_16x16x32_bf16 v[58:61], v[148:151], v[164:167], v[58:61]
	v_mfma_f32_16x16x32_bf16 v[54:57], v[156:159], v[164:167], v[54:57]
	v_mfma_f32_16x16x32_bf16 v[50:53], v[148:151], v[172:175], v[50:53]
	v_mfma_f32_16x16x32_bf16 v[46:49], v[156:159], v[172:175], v[46:49]
	v_mfma_f32_16x16x32_bf16 v[42:45], v[148:151], v[180:183], v[42:45]
	v_mfma_f32_16x16x32_bf16 v[38:41], v[156:159], v[180:183], v[38:41]
	v_mfma_f32_16x16x32_bf16 v[34:37], v[148:151], v[188:191], v[34:37]
	v_mfma_f32_16x16x32_bf16 v[30:33], v[156:159], v[188:191], v[30:33]
	v_mfma_f32_16x16x32_bf16 v[26:29], v[192:195], v[160:163], v[26:29]
	v_mfma_f32_16x16x32_bf16 v[22:25], v[202:205], v[160:163], v[22:25]
	v_mfma_f32_16x16x32_bf16 v[18:21], v[192:195], v[168:171], v[18:21]
	v_mfma_f32_16x16x32_bf16 v[14:17], v[202:205], v[168:171], v[14:17]
	v_mfma_f32_16x16x32_bf16 v[10:13], v[192:195], v[176:179], v[10:13]
	v_mfma_f32_16x16x32_bf16 v[6:9], v[202:205], v[176:179], v[6:9]
	v_mfma_f32_16x16x32_bf16 v[2:5], v[192:195], v[184:187], v[2:5]
	v_mfma_f32_16x16x32_bf16 v[74:77], v[202:205], v[184:187], v[74:77]
	v_mfma_f32_16x16x32_bf16 v[26:29], v[198:201], v[164:167], v[26:29]
	v_mfma_f32_16x16x32_bf16 v[22:25], v[206:209], v[164:167], v[22:25]
	v_mfma_f32_16x16x32_bf16 v[18:21], v[198:201], v[172:175], v[18:21]
	v_mfma_f32_16x16x32_bf16 v[14:17], v[206:209], v[172:175], v[14:17]
	v_mfma_f32_16x16x32_bf16 v[10:13], v[198:201], v[180:183], v[10:13]
	v_mfma_f32_16x16x32_bf16 v[6:9], v[206:209], v[180:183], v[6:9]
	v_mfma_f32_16x16x32_bf16 v[2:5], v[198:201], v[188:191], v[2:5]
	v_mfma_f32_16x16x32_bf16 v[74:77], v[206:209], v[188:191], v[74:77]
	s_setprio 0
	s_add_i32 s41, 0, 0x18000
	s_barrier
	v_add_u32_e32 v156, 0x18000, v143
	ds_read_b128 v[144:147], v156
	ds_read_b128 v[148:151], v156 offset:1024
	ds_read_b128 v[152:155], v156 offset:2048
	ds_read_b128 v[156:159], v156 offset:3072
	ds_read_b128 v[160:163], v142 offset:32768
	ds_read_b128 v[164:167], v142 offset:33792
	ds_read_b128 v[168:171], v142 offset:34816
	ds_read_b128 v[172:175], v142 offset:35840
	ds_read_b128 v[176:179], v142 offset:36864
	ds_read_b128 v[180:183], v142 offset:37888
	ds_read_b128 v[184:187], v142 offset:38912
	ds_read_b128 v[188:191], v142 offset:39936
	s_mov_b32 m0, s78
	v_lshl_add_u64 v[192:193], v[210:211], 0, s[18:19]
	global_load_lds_dwordx4 v[192:193], off
	v_lshl_add_u64 v[192:193], v[212:213], 0, s[18:19]
	s_mov_b32 m0, s79
	s_nop 0
	global_load_lds_dwordx4 v[192:193], off
	v_add_u32_e32 v197, 0x1c000, v143
	ds_read_b128 v[192:195], v197
	ds_read_b128 v[198:201], v197 offset:1024
	ds_read_b128 v[202:205], v197 offset:2048
	ds_read_b128 v[206:209], v197 offset:3072
	s_waitcnt vmcnt(8)
	s_waitcnt lgkmcnt(0)
	s_barrier
	s_setprio 1
	v_mfma_f32_16x16x32_bf16 v[126:129], v[144:147], v[160:163], v[126:129]
	v_mfma_f32_16x16x32_bf16 v[122:125], v[152:155], v[160:163], v[122:125]
	v_mfma_f32_16x16x32_bf16 v[118:121], v[144:147], v[168:171], v[118:121]
	v_mfma_f32_16x16x32_bf16 v[114:117], v[152:155], v[168:171], v[114:117]
	v_mfma_f32_16x16x32_bf16 v[110:113], v[144:147], v[176:179], v[110:113]
	v_mfma_f32_16x16x32_bf16 v[106:109], v[152:155], v[176:179], v[106:109]
	v_mfma_f32_16x16x32_bf16 v[102:105], v[144:147], v[184:187], v[102:105]
	v_mfma_f32_16x16x32_bf16 v[98:101], v[152:155], v[184:187], v[98:101]
	v_mfma_f32_16x16x32_bf16 v[126:129], v[148:151], v[164:167], v[126:129]
	v_mfma_f32_16x16x32_bf16 v[122:125], v[156:159], v[164:167], v[122:125]
	v_mfma_f32_16x16x32_bf16 v[118:121], v[148:151], v[172:175], v[118:121]
	v_mfma_f32_16x16x32_bf16 v[114:117], v[156:159], v[172:175], v[114:117]
	v_mfma_f32_16x16x32_bf16 v[110:113], v[148:151], v[180:183], v[110:113]
	v_mfma_f32_16x16x32_bf16 v[106:109], v[156:159], v[180:183], v[106:109]
	v_mfma_f32_16x16x32_bf16 v[102:105], v[148:151], v[188:191], v[102:105]
	v_mfma_f32_16x16x32_bf16 v[98:101], v[156:159], v[188:191], v[98:101]
	v_mfma_f32_16x16x32_bf16 v[94:97], v[192:195], v[160:163], v[94:97]
	v_mfma_f32_16x16x32_bf16 v[90:93], v[202:205], v[160:163], v[90:93]
	v_mfma_f32_16x16x32_bf16 v[86:89], v[192:195], v[168:171], v[86:89]
	v_mfma_f32_16x16x32_bf16 v[82:85], v[202:205], v[168:171], v[82:85]
	v_mfma_f32_16x16x32_bf16 v[78:81], v[192:195], v[176:179], v[78:81]
	v_mfma_f32_16x16x32_bf16 v[70:73], v[202:205], v[176:179], v[70:73]
	v_mfma_f32_16x16x32_bf16 v[66:69], v[192:195], v[184:187], v[66:69]
	v_mfma_f32_16x16x32_bf16 v[62:65], v[202:205], v[184:187], v[62:65]
	v_mfma_f32_16x16x32_bf16 v[94:97], v[198:201], v[164:167], v[94:97]
	v_mfma_f32_16x16x32_bf16 v[90:93], v[206:209], v[164:167], v[90:93]
	v_mfma_f32_16x16x32_bf16 v[86:89], v[198:201], v[172:175], v[86:89]
	v_mfma_f32_16x16x32_bf16 v[82:85], v[206:209], v[172:175], v[82:85]
	v_mfma_f32_16x16x32_bf16 v[78:81], v[198:201], v[180:183], v[78:81]
	v_mfma_f32_16x16x32_bf16 v[70:73], v[206:209], v[180:183], v[70:73]
	v_mfma_f32_16x16x32_bf16 v[66:69], v[198:201], v[188:191], v[66:69]
	v_mfma_f32_16x16x32_bf16 v[62:65], v[206:209], v[188:191], v[62:65]
	s_setprio 0
	s_mov_b32 m0, s74
	v_lshl_add_u64 v[210:211], v[210:211], 0, s[54:55]
	s_barrier
	ds_read_b128 v[160:163], v142 offset:49152
	ds_read_b128 v[164:167], v142 offset:50176
	ds_read_b128 v[168:171], v142 offset:51200
	ds_read_b128 v[172:175], v142 offset:52224
	ds_read_b128 v[176:179], v142 offset:53248
	ds_read_b128 v[180:183], v142 offset:54272
	ds_read_b128 v[184:187], v142 offset:55296
	ds_read_b128 v[188:191], v142 offset:56320
	global_load_lds_dwordx4 v[210:211], off
	v_lshl_add_u64 v[210:211], v[212:213], 0, s[54:55]
	s_mov_b32 m0, vcc_lo
	s_nop 0
	global_load_lds_dwordx4 v[210:211], off
	s_add_i32 s70, 0, 0x1c000
	s_add_i32 s41, s41, s42
	v_lshl_add_u64 v[218:219], v[214:215], 0, s[52:53]
	s_mov_b32 m0, s41
	s_nop 0
	global_load_lds_dwordx4 v[218:219], off
	v_lshl_add_u64 v[218:219], v[216:217], 0, s[52:53]
	s_add_i32 m0, s41, 0x2000
	s_nop 0
	global_load_lds_dwordx4 v[218:219], off
	s_add_i32 s41, s70, s42
	v_lshl_add_u64 v[218:219], v[214:215], 0, s[56:57]
	s_mov_b32 m0, s41
	s_nop 0
	global_load_lds_dwordx4 v[218:219], off
	v_lshl_add_u64 v[218:219], v[216:217], 0, s[56:57]
	s_add_i32 m0, s41, 0x2000
	s_nop 0
	global_load_lds_dwordx4 v[218:219], off
	s_waitcnt vmcnt(8)
	s_waitcnt lgkmcnt(0)
	s_barrier
	s_setprio 1
	v_mfma_f32_16x16x32_bf16 v[58:61], v[144:147], v[160:163], v[58:61]
	v_mfma_f32_16x16x32_bf16 v[54:57], v[152:155], v[160:163], v[54:57]
	v_mfma_f32_16x16x32_bf16 v[50:53], v[144:147], v[168:171], v[50:53]
	v_mfma_f32_16x16x32_bf16 v[46:49], v[152:155], v[168:171], v[46:49]
	v_mfma_f32_16x16x32_bf16 v[42:45], v[144:147], v[176:179], v[42:45]
	v_mfma_f32_16x16x32_bf16 v[38:41], v[152:155], v[176:179], v[38:41]
	v_mfma_f32_16x16x32_bf16 v[34:37], v[144:147], v[184:187], v[34:37]
	v_mfma_f32_16x16x32_bf16 v[30:33], v[152:155], v[184:187], v[30:33]
	v_mfma_f32_16x16x32_bf16 v[58:61], v[148:151], v[164:167], v[58:61]
	v_mfma_f32_16x16x32_bf16 v[54:57], v[156:159], v[164:167], v[54:57]
	v_mfma_f32_16x16x32_bf16 v[50:53], v[148:151], v[172:175], v[50:53]
	v_mfma_f32_16x16x32_bf16 v[46:49], v[156:159], v[172:175], v[46:49]
	v_mfma_f32_16x16x32_bf16 v[42:45], v[148:151], v[180:183], v[42:45]
	v_mfma_f32_16x16x32_bf16 v[38:41], v[156:159], v[180:183], v[38:41]
	v_mfma_f32_16x16x32_bf16 v[34:37], v[148:151], v[188:191], v[34:37]
	v_mfma_f32_16x16x32_bf16 v[30:33], v[156:159], v[188:191], v[30:33]
	v_mfma_f32_16x16x32_bf16 v[26:29], v[192:195], v[160:163], v[26:29]
	v_mfma_f32_16x16x32_bf16 v[22:25], v[202:205], v[160:163], v[22:25]
	v_mfma_f32_16x16x32_bf16 v[18:21], v[192:195], v[168:171], v[18:21]
	v_mfma_f32_16x16x32_bf16 v[14:17], v[202:205], v[168:171], v[14:17]
	v_mfma_f32_16x16x32_bf16 v[10:13], v[192:195], v[176:179], v[10:13]
	v_mfma_f32_16x16x32_bf16 v[6:9], v[202:205], v[176:179], v[6:9]
	v_mfma_f32_16x16x32_bf16 v[2:5], v[192:195], v[184:187], v[2:5]
	v_mfma_f32_16x16x32_bf16 v[74:77], v[202:205], v[184:187], v[74:77]
	v_mfma_f32_16x16x32_bf16 v[26:29], v[198:201], v[164:167], v[26:29]
	v_mfma_f32_16x16x32_bf16 v[22:25], v[206:209], v[164:167], v[22:25]
	v_mfma_f32_16x16x32_bf16 v[18:21], v[198:201], v[172:175], v[18:21]
	v_mfma_f32_16x16x32_bf16 v[14:17], v[206:209], v[172:175], v[14:17]
	v_mfma_f32_16x16x32_bf16 v[10:13], v[198:201], v[180:183], v[10:13]
	v_mfma_f32_16x16x32_bf16 v[6:9], v[206:209], v[180:183], v[6:9]
	v_mfma_f32_16x16x32_bf16 v[2:5], v[198:201], v[188:191], v[2:5]
	v_mfma_f32_16x16x32_bf16 v[74:77], v[206:209], v[188:191], v[74:77]
	s_setprio 0
	s_add_i32 s36, s36, 2
	v_lshl_add_u64 v[134:135], v[134:135], 0, s[98:99]
	v_lshl_add_u64 v[136:137], v[136:137], 0, s[98:99]
	v_lshl_add_u64 v[138:139], v[138:139], 0, s[98:99]
	s_cmp_gt_u32 s36, 39
	v_lshl_add_u64 v[140:141], v[140:141], 0, s[98:99]
	s_barrier
	s_cbranch_scc0 .LBB0_95
	s_waitcnt vmcnt(6)
	s_add_u32 s16, s16, 0xb1580
	v_add_u32_e32 v143, 0, v143
	s_addc_u32 s17, s17, 0
	s_mov_b32 m0, s40
	v_add_u32_e32 v148, 0x10000, v143
	v_lshl_add_u64 v[130:131], s[16:17], 0, v[130:131]
	ds_read_b128 v[134:137], v148
	ds_read_b128 v[138:141], v148 offset:1024
	ds_read_b128 v[144:147], v148 offset:2048
	ds_read_b128 v[148:151], v148 offset:3072
	ds_read_b128 v[152:155], v142
	ds_read_b128 v[156:159], v142 offset:1024
	ds_read_b128 v[160:163], v142 offset:2048
	ds_read_b128 v[164:167], v142 offset:3072
	ds_read_b128 v[168:171], v142 offset:4096
	ds_read_b128 v[172:175], v142 offset:5120
	ds_read_b128 v[176:179], v142 offset:6144
	ds_read_b128 v[180:183], v142 offset:7168
	global_load_lds_dwordx4 v[130:131], off
	v_lshl_add_u64 v[130:131], s[16:17], 0, v[132:133]
	s_mov_b32 m0, s37
	s_nop 0
	global_load_lds_dwordx4 v[130:131], off
	s_barrier
	s_waitcnt lgkmcnt(0)
	s_setprio 1
	s_waitcnt lgkmcnt(0)
	v_mfma_f32_16x16x32_bf16 v[126:129], v[134:137], v[152:155], v[126:129]
	v_mfma_f32_16x16x32_bf16 v[122:125], v[144:147], v[152:155], v[122:125]
	v_mfma_f32_16x16x32_bf16 v[118:121], v[134:137], v[160:163], v[118:121]
	v_mfma_f32_16x16x32_bf16 v[114:117], v[144:147], v[160:163], v[114:117]
	v_mfma_f32_16x16x32_bf16 v[102:105], v[134:137], v[176:179], v[102:105]
	v_mfma_f32_16x16x32_bf16 v[126:129], v[138:141], v[156:159], v[126:129]
	v_mfma_f32_16x16x32_bf16 v[122:125], v[148:151], v[156:159], v[122:125]
	v_mfma_f32_16x16x32_bf16 v[118:121], v[138:141], v[164:167], v[118:121]
	v_mfma_f32_16x16x32_bf16 v[114:117], v[148:151], v[164:167], v[114:117]
	v_mfma_f32_16x16x32_bf16 v[110:113], v[134:137], v[168:171], v[110:113]
	v_mfma_f32_16x16x32_bf16 v[106:109], v[144:147], v[168:171], v[106:109]
	v_mfma_f32_16x16x32_bf16 v[102:105], v[138:141], v[180:183], v[102:105]
	v_mfma_f32_16x16x32_bf16 v[98:101], v[144:147], v[176:179], v[98:101]
	v_mfma_f32_16x16x32_bf16 v[110:113], v[138:141], v[172:175], v[110:113]
	v_mfma_f32_16x16x32_bf16 v[106:109], v[148:151], v[172:175], v[106:109]
	v_mfma_f32_16x16x32_bf16 v[130:133], v[148:151], v[180:183], v[98:101]
	s_setprio 0
	v_add_u32_e32 v192, 0x14000, v143
	s_barrier
	s_nop 1
	ds_read_b128 v[98:101], v192
	ds_read_b128 v[184:187], v192 offset:1024
	ds_read_b128 v[188:191], v192 offset:2048
	ds_read_b128 v[192:195], v192 offset:3072
	s_barrier
	s_waitcnt lgkmcnt(0)
	s_setprio 1
	s_waitcnt lgkmcnt(0)
	v_mfma_f32_16x16x32_bf16 v[94:97], v[98:101], v[152:155], v[94:97]
	v_mfma_f32_16x16x32_bf16 v[82:85], v[188:191], v[160:163], v[82:85]
	v_mfma_f32_16x16x32_bf16 v[62:65], v[188:191], v[176:179], v[62:65]
	v_mfma_f32_16x16x32_bf16 v[94:97], v[184:187], v[156:159], v[94:97]
	v_mfma_f32_16x16x32_bf16 v[90:93], v[188:191], v[152:155], v[90:93]
	v_mfma_f32_16x16x32_bf16 v[86:89], v[98:101], v[160:163], v[86:89]
	v_mfma_f32_16x16x32_bf16 v[82:85], v[192:195], v[164:167], v[82:85]
	v_mfma_f32_16x16x32_bf16 v[78:81], v[98:101], v[168:171], v[78:81]
	v_mfma_f32_16x16x32_bf16 v[70:73], v[188:191], v[168:171], v[70:73]
	v_mfma_f32_16x16x32_bf16 v[66:69], v[98:101], v[176:179], v[66:69]
	v_mfma_f32_16x16x32_bf16 v[62:65], v[192:195], v[180:183], v[62:65]
	v_mfma_f32_16x16x32_bf16 v[198:201], v[192:195], v[156:159], v[90:93]
	v_mfma_f32_16x16x32_bf16 v[86:89], v[184:187], v[164:167], v[86:89]
	v_mfma_f32_16x16x32_bf16 v[164:167], v[184:187], v[172:175], v[78:81]
	v_mfma_f32_16x16x32_bf16 v[168:171], v[192:195], v[172:175], v[70:73]
	v_mfma_f32_16x16x32_bf16 v[66:69], v[184:187], v[180:183], v[66:69]
	s_setprio 0
	s_barrier
	ds_read_b128 v[70:73], v142 offset:16384
	ds_read_b128 v[78:81], v142 offset:17408
	ds_read_b128 v[90:93], v142 offset:18432
	ds_read_b128 v[152:155], v142 offset:19456
	ds_read_b128 v[156:159], v142 offset:20480
	ds_read_b128 v[160:163], v142 offset:21504
	ds_read_b128 v[172:175], v142 offset:22528
	ds_read_b128 v[176:179], v142 offset:23552
	s_waitcnt vmcnt(4)
	s_barrier
	s_waitcnt lgkmcnt(0)
	s_setprio 1
	s_waitcnt lgkmcnt(0)
	v_mfma_f32_16x16x32_bf16 v[58:61], v[134:137], v[70:73], v[58:61]
	v_mfma_f32_16x16x32_bf16 v[54:57], v[144:147], v[70:73], v[54:57]
	v_mfma_f32_16x16x32_bf16 v[50:53], v[134:137], v[90:93], v[50:53]
	v_mfma_f32_16x16x32_bf16 v[42:45], v[134:137], v[156:159], v[42:45]
	v_mfma_f32_16x16x32_bf16 v[34:37], v[134:137], v[172:175], v[34:37]
	v_mfma_f32_16x16x32_bf16 v[58:61], v[138:141], v[78:81], v[58:61]
	v_mfma_f32_16x16x32_bf16 v[54:57], v[148:151], v[78:81], v[54:57]
	v_mfma_f32_16x16x32_bf16 v[50:53], v[138:141], v[152:155], v[50:53]
	v_mfma_f32_16x16x32_bf16 v[46:49], v[144:147], v[90:93], v[46:49]
	v_mfma_f32_16x16x32_bf16 v[42:45], v[138:141], v[160:163], v[42:45]
	v_mfma_f32_16x16x32_bf16 v[38:41], v[144:147], v[156:159], v[38:41]
	v_mfma_f32_16x16x32_bf16 v[34:37], v[138:141], v[176:179], v[34:37]
	v_mfma_f32_16x16x32_bf16 v[30:33], v[144:147], v[172:175], v[30:33]
	v_mfma_f32_16x16x32_bf16 v[180:183], v[148:151], v[152:155], v[46:49]
	v_mfma_f32_16x16x32_bf16 v[202:205], v[148:151], v[160:163], v[38:41]
	v_mfma_f32_16x16x32_bf16 v[134:137], v[148:151], v[176:179], v[30:33]
	s_setprio 0
	s_setprio 1
	v_mfma_f32_16x16x32_bf16 v[26:29], v[98:101], v[70:73], v[26:29]
	v_mfma_f32_16x16x32_bf16 v[18:21], v[98:101], v[90:93], v[18:21]
	v_mfma_f32_16x16x32_bf16 v[10:13], v[98:101], v[156:159], v[10:13]
	v_mfma_f32_16x16x32_bf16 v[6:9], v[188:191], v[156:159], v[6:9]
	v_mfma_f32_16x16x32_bf16 v[2:5], v[98:101], v[172:175], v[2:5]
	v_mfma_f32_16x16x32_bf16 v[26:29], v[184:187], v[78:81], v[26:29]
	v_mfma_f32_16x16x32_bf16 v[22:25], v[188:191], v[70:73], v[22:25]
	v_mfma_f32_16x16x32_bf16 v[18:21], v[184:187], v[152:155], v[18:21]
	v_mfma_f32_16x16x32_bf16 v[14:17], v[188:191], v[90:93], v[14:17]
	v_mfma_f32_16x16x32_bf16 v[10:13], v[184:187], v[160:163], v[10:13]
	v_mfma_f32_16x16x32_bf16 v[206:209], v[192:195], v[160:163], v[6:9]
	v_mfma_f32_16x16x32_bf16 v[2:5], v[184:187], v[176:179], v[2:5]
	v_mfma_f32_16x16x32_bf16 v[6:9], v[188:191], v[172:175], v[74:77]
	v_mfma_f32_16x16x32_bf16 v[138:141], v[192:195], v[78:81], v[22:25]
	v_mfma_f32_16x16x32_bf16 v[144:147], v[192:195], v[152:155], v[14:17]
	v_mfma_f32_16x16x32_bf16 v[172:175], v[192:195], v[176:179], v[6:9]
	s_setprio 0
	v_add_u32_e32 v22, 0x18000, v143
	s_barrier
	s_nop 1
	ds_read_b128 v[6:9], v22
	ds_read_b128 v[14:17], v22 offset:1024
	ds_read_b128 v[176:179], v22 offset:2048
	ds_read_b128 v[184:187], v22 offset:3072
	ds_read_b128 v[22:25], v142 offset:32768
	ds_read_b128 v[30:33], v142 offset:33792
	ds_read_b128 v[38:41], v142 offset:34816
	ds_read_b128 v[46:49], v142 offset:35840
	ds_read_b128 v[74:77], v142 offset:36864
	ds_read_b128 v[188:191], v142 offset:37888
	ds_read_b128 v[192:195], v142 offset:38912
	ds_read_b128 v[210:213], v142 offset:39936
	s_waitcnt vmcnt(2)
	s_barrier
	s_waitcnt lgkmcnt(0)
	s_setprio 1
	s_waitcnt lgkmcnt(0)
	v_mfma_f32_16x16x32_bf16 v[70:73], v[6:9], v[22:25], v[126:129]
	v_mfma_f32_16x16x32_bf16 v[152:155], v[14:17], v[30:33], v[70:73]
	v_mfma_f32_16x16x32_bf16 v[70:73], v[176:179], v[22:25], v[122:125]
	v_mfma_f32_16x16x32_bf16 v[160:163], v[184:187], v[30:33], v[70:73]
	v_mfma_f32_16x16x32_bf16 v[70:73], v[6:9], v[38:41], v[118:121]
	v_mfma_f32_16x16x32_bf16 v[122:125], v[14:17], v[46:49], v[70:73]
	v_mfma_f32_16x16x32_bf16 v[70:73], v[176:179], v[38:41], v[114:117]
	v_mfma_f32_16x16x32_bf16 v[114:117], v[184:187], v[46:49], v[70:73]
	v_mfma_f32_16x16x32_bf16 v[70:73], v[6:9], v[74:77], v[110:113]
	v_mfma_f32_16x16x32_bf16 v[98:101], v[14:17], v[188:191], v[70:73]
	v_mfma_f32_16x16x32_bf16 v[70:73], v[176:179], v[74:77], v[106:109]
	v_mfma_f32_16x16x32_bf16 v[90:93], v[184:187], v[188:191], v[70:73]
	v_mfma_f32_16x16x32_bf16 v[70:73], v[6:9], v[192:195], v[102:105]
	v_mfma_f32_16x16x32_bf16 v[78:81], v[14:17], v[210:213], v[70:73]
	v_mfma_f32_16x16x32_bf16 v[70:73], v[176:179], v[192:195], v[130:133]
	v_mfma_f32_16x16x32_bf16 v[70:73], v[184:187], v[210:213], v[70:73]
	s_setprio 0
	v_add_u32_e32 v102, 0x1c000, v143
	s_barrier
	ds_read_b128 v[106:109], v102
	ds_read_b128 v[110:113], v102 offset:1024
	ds_read_b128 v[130:133], v102 offset:2048
	ds_read_b128 v[214:217], v102 offset:3072
	s_waitcnt vmcnt(0)
	s_barrier
	s_waitcnt lgkmcnt(0)
	s_setprio 1
	s_waitcnt lgkmcnt(0)
	v_mfma_f32_16x16x32_bf16 v[94:97], v[106:109], v[22:25], v[94:97]
	v_mfma_f32_16x16x32_bf16 v[22:25], v[130:133], v[22:25], v[198:201]
	v_mfma_f32_16x16x32_bf16 v[148:151], v[214:217], v[30:33], v[22:25]
	v_mfma_f32_16x16x32_bf16 v[22:25], v[106:109], v[38:41], v[86:89]
	v_mfma_f32_16x16x32_bf16 v[126:129], v[110:113], v[46:49], v[22:25]
	v_mfma_f32_16x16x32_bf16 v[22:25], v[130:133], v[38:41], v[82:85]
	v_mfma_f32_16x16x32_bf16 v[118:121], v[214:217], v[46:49], v[22:25]
	v_mfma_f32_16x16x32_bf16 v[22:25], v[106:109], v[74:77], v[164:167]
	v_mfma_f32_16x16x32_bf16 v[102:105], v[110:113], v[188:191], v[22:25]
	v_mfma_f32_16x16x32_bf16 v[22:25], v[130:133], v[74:77], v[168:171]
	v_mfma_f32_16x16x32_bf16 v[156:159], v[110:113], v[30:33], v[94:97]
	v_mfma_f32_16x16x32_bf16 v[94:97], v[214:217], v[188:191], v[22:25]
	v_mfma_f32_16x16x32_bf16 v[22:25], v[106:109], v[192:195], v[66:69]
	v_mfma_f32_16x16x32_bf16 v[82:85], v[110:113], v[210:213], v[22:25]
	v_mfma_f32_16x16x32_bf16 v[22:25], v[130:133], v[192:195], v[62:65]
	v_mfma_f32_16x16x32_bf16 v[74:77], v[214:217], v[210:213], v[22:25]
	s_setprio 0
	s_barrier
	ds_read_b128 v[66:69], v142 offset:49152
	ds_read_b128 v[86:89], v142 offset:50176
	ds_read_b128 v[164:167], v142 offset:51200
	ds_read_b128 v[168:171], v142 offset:52224
	ds_read_b128 v[188:191], v142 offset:53248
	ds_read_b128 v[192:195], v142 offset:54272
	ds_read_b128 v[198:201], v142 offset:55296
	ds_read_b128 v[210:213], v142 offset:56320
	s_barrier
	s_waitcnt lgkmcnt(0)
	s_setprio 1
	s_waitcnt lgkmcnt(0)
	v_mfma_f32_16x16x32_bf16 v[22:25], v[6:9], v[66:69], v[58:61]
	v_mfma_f32_16x16x32_bf16 v[62:65], v[14:17], v[86:89], v[22:25]
	v_mfma_f32_16x16x32_bf16 v[22:25], v[176:179], v[66:69], v[54:57]
	v_mfma_f32_16x16x32_bf16 v[54:57], v[184:187], v[86:89], v[22:25]
	v_mfma_f32_16x16x32_bf16 v[22:25], v[6:9], v[164:167], v[50:53]
	v_mfma_f32_16x16x32_bf16 v[46:49], v[14:17], v[168:171], v[22:25]
	v_mfma_f32_16x16x32_bf16 v[22:25], v[176:179], v[164:167], v[180:183]
	v_mfma_f32_16x16x32_bf16 v[38:41], v[184:187], v[168:171], v[22:25]
	v_mfma_f32_16x16x32_bf16 v[22:25], v[6:9], v[188:191], v[42:45]
	v_mfma_f32_16x16x32_bf16 v[6:9], v[6:9], v[198:201], v[34:37]
	v_mfma_f32_16x16x32_bf16 v[30:33], v[14:17], v[192:195], v[22:25]
	v_mfma_f32_16x16x32_bf16 v[22:25], v[176:179], v[188:191], v[202:205]
	v_mfma_f32_16x16x32_bf16 v[14:17], v[14:17], v[210:213], v[6:9]
	v_mfma_f32_16x16x32_bf16 v[6:9], v[176:179], v[198:201], v[134:137]
	v_mfma_f32_16x16x32_bf16 v[22:25], v[184:187], v[192:195], v[22:25]
	v_mfma_f32_16x16x32_bf16 v[6:9], v[184:187], v[210:213], v[6:9]
	s_setprio 0
	s_setprio 1
	v_mfma_f32_16x16x32_bf16 v[26:29], v[106:109], v[66:69], v[26:29]
	v_mfma_f32_16x16x32_bf16 v[58:61], v[110:113], v[86:89], v[26:29]
	v_mfma_f32_16x16x32_bf16 v[26:29], v[130:133], v[66:69], v[138:141]
	v_mfma_f32_16x16x32_bf16 v[18:21], v[106:109], v[164:167], v[18:21]
	v_mfma_f32_16x16x32_bf16 v[10:13], v[106:109], v[188:191], v[10:13]
	v_mfma_f32_16x16x32_bf16 v[50:53], v[214:217], v[86:89], v[26:29]
	v_mfma_f32_16x16x32_bf16 v[42:45], v[110:113], v[168:171], v[18:21]
	v_mfma_f32_16x16x32_bf16 v[18:21], v[130:133], v[164:167], v[144:147]
	v_mfma_f32_16x16x32_bf16 v[26:29], v[110:113], v[192:195], v[10:13]
	v_mfma_f32_16x16x32_bf16 v[10:13], v[130:133], v[188:191], v[206:209]
	v_mfma_f32_16x16x32_bf16 v[2:5], v[106:109], v[198:201], v[2:5]
	v_mfma_f32_16x16x32_bf16 v[34:37], v[214:217], v[168:171], v[18:21]
	v_mfma_f32_16x16x32_bf16 v[18:21], v[214:217], v[192:195], v[10:13]
	v_mfma_f32_16x16x32_bf16 v[10:13], v[110:113], v[210:213], v[2:5]
	v_mfma_f32_16x16x32_bf16 v[2:5], v[130:133], v[198:201], v[172:175]
	v_mfma_f32_16x16x32_bf16 v[2:5], v[214:217], v[210:213], v[2:5]
	s_setprio 0
	s_cmpk_lt_u32 s2, 0x100
	s_movk_i32 s75, 0x410
	s_movk_i32 s76, 0xfbfc
	s_barrier
	s_cbranch_scc0 .LBB0_98
	s_barrier

.LBB0_161:
	v_add_u32_e32 v156, 0x10000, v143
	ds_read_b128 v[144:147], v156
	ds_read_b128 v[148:151], v156 offset:1024
	ds_read_b128 v[152:155], v156 offset:2048
	ds_read_b128 v[156:159], v156 offset:3072
	ds_read_b128 v[160:163], v142
	ds_read_b128 v[164:167], v142 offset:1024
	ds_read_b128 v[168:171], v142 offset:2048
	ds_read_b128 v[172:175], v142 offset:3072
	ds_read_b128 v[176:179], v142 offset:4096
	ds_read_b128 v[180:183], v142 offset:5120
	ds_read_b128 v[184:187], v142 offset:6144
	ds_read_b128 v[188:191], v142 offset:7168
	s_add_i32 s41, 0, 0x10000
	v_lshl_add_u64 v[210:211], v[138:139], 0, s[14:15]
	s_add_i32 s40, s43, 0xc000
	v_lshl_add_u64 v[192:193], v[210:211], 0, s[20:21]
	s_mov_b32 m0, s40
	v_lshl_add_u64 v[212:213], v[140:141], 0, s[14:15]
	s_add_i32 s17, s43, 0xe000
	global_load_lds_dwordx4 v[192:193], off
	v_lshl_add_u64 v[192:193], v[212:213], 0, s[20:21]
	s_mov_b32 m0, s17
	s_nop 0
	global_load_lds_dwordx4 v[192:193], off
	v_add_u32_e32 v197, 0x14000, v143
	ds_read_b128 v[192:195], v197
	ds_read_b128 v[198:201], v197 offset:1024
	ds_read_b128 v[202:205], v197 offset:2048
	ds_read_b128 v[206:209], v197 offset:3072
	s_waitcnt vmcnt(8)
	s_waitcnt lgkmcnt(0)
	s_barrier
	s_setprio 1
	v_mfma_f32_16x16x32_bf16 v[126:129], v[144:147], v[160:163], v[126:129]
	v_mfma_f32_16x16x32_bf16 v[122:125], v[152:155], v[160:163], v[122:125]
	v_mfma_f32_16x16x32_bf16 v[118:121], v[144:147], v[168:171], v[118:121]
	v_mfma_f32_16x16x32_bf16 v[114:117], v[152:155], v[168:171], v[114:117]
	v_mfma_f32_16x16x32_bf16 v[110:113], v[144:147], v[176:179], v[110:113]
	v_mfma_f32_16x16x32_bf16 v[106:109], v[152:155], v[176:179], v[106:109]
	v_mfma_f32_16x16x32_bf16 v[102:105], v[144:147], v[184:187], v[102:105]
	v_mfma_f32_16x16x32_bf16 v[98:101], v[152:155], v[184:187], v[98:101]
	v_mfma_f32_16x16x32_bf16 v[126:129], v[148:151], v[164:167], v[126:129]
	v_mfma_f32_16x16x32_bf16 v[122:125], v[156:159], v[164:167], v[122:125]
	v_mfma_f32_16x16x32_bf16 v[118:121], v[148:151], v[172:175], v[118:121]
	v_mfma_f32_16x16x32_bf16 v[114:117], v[156:159], v[172:175], v[114:117]
	v_mfma_f32_16x16x32_bf16 v[110:113], v[148:151], v[180:183], v[110:113]
	v_mfma_f32_16x16x32_bf16 v[106:109], v[156:159], v[180:183], v[106:109]
	v_mfma_f32_16x16x32_bf16 v[102:105], v[148:151], v[188:191], v[102:105]
	v_mfma_f32_16x16x32_bf16 v[98:101], v[156:159], v[188:191], v[98:101]
	v_mfma_f32_16x16x32_bf16 v[94:97], v[192:195], v[160:163], v[94:97]
	v_mfma_f32_16x16x32_bf16 v[90:93], v[202:205], v[160:163], v[90:93]
	v_mfma_f32_16x16x32_bf16 v[78:81], v[192:195], v[168:171], v[78:81]
	v_mfma_f32_16x16x32_bf16 v[62:65], v[202:205], v[168:171], v[62:65]
	v_mfma_f32_16x16x32_bf16 v[58:61], v[192:195], v[176:179], v[58:61]
	v_mfma_f32_16x16x32_bf16 v[54:57], v[202:205], v[176:179], v[54:57]
	v_mfma_f32_16x16x32_bf16 v[50:53], v[192:195], v[184:187], v[50:53]
	v_mfma_f32_16x16x32_bf16 v[46:49], v[202:205], v[184:187], v[46:49]
	v_mfma_f32_16x16x32_bf16 v[94:97], v[198:201], v[164:167], v[94:97]
	v_mfma_f32_16x16x32_bf16 v[90:93], v[206:209], v[164:167], v[90:93]
	v_mfma_f32_16x16x32_bf16 v[78:81], v[198:201], v[172:175], v[78:81]
	v_mfma_f32_16x16x32_bf16 v[62:65], v[206:209], v[172:175], v[62:65]
	v_mfma_f32_16x16x32_bf16 v[58:61], v[198:201], v[180:183], v[58:61]
	v_mfma_f32_16x16x32_bf16 v[54:57], v[206:209], v[180:183], v[54:57]
	v_mfma_f32_16x16x32_bf16 v[50:53], v[198:201], v[188:191], v[50:53]
	v_mfma_f32_16x16x32_bf16 v[46:49], v[206:209], v[188:191], v[46:49]
	s_setprio 0
	s_mov_b32 m0, s43
	v_lshl_add_u64 v[218:219], v[210:211], 0, s[24:25]
	s_barrier
	ds_read_b128 v[160:163], v142 offset:16384
	ds_read_b128 v[164:167], v142 offset:17408
	ds_read_b128 v[168:171], v142 offset:18432
	ds_read_b128 v[172:175], v142 offset:19456
	ds_read_b128 v[176:179], v142 offset:20480
	ds_read_b128 v[180:183], v142 offset:21504
	ds_read_b128 v[184:187], v142 offset:22528
	ds_read_b128 v[188:191], v142 offset:23552
	global_load_lds_dwordx4 v[218:219], off
	v_lshl_add_u64 v[218:219], v[212:213], 0, s[24:25]
	s_mov_b32 m0, s73
	s_nop 0
	global_load_lds_dwordx4 v[218:219], off
	s_add_i32 s44, 0, 0x14000
	v_lshl_add_u64 v[214:215], v[134:135], 0, s[14:15]
	s_add_i32 s41, s41, s37
	v_lshl_add_u64 v[216:217], v[214:215], 0, s[22:23]
	s_mov_b32 m0, s41
	s_nop 0
	global_load_lds_dwordx4 v[216:217], off
	v_lshl_add_u64 v[216:217], v[136:137], 0, s[14:15]
	v_lshl_add_u64 v[218:219], v[216:217], 0, s[22:23]
	s_add_i32 m0, s41, 0x2000
	s_nop 0
	global_load_lds_dwordx4 v[218:219], off
	s_add_i32 s41, s44, s37
	v_lshl_add_u64 v[218:219], v[214:215], 0, s[26:27]
	s_mov_b32 m0, s41
	s_nop 0
	global_load_lds_dwordx4 v[218:219], off
	v_lshl_add_u64 v[218:219], v[216:217], 0, s[26:27]
	s_add_i32 m0, s41, 0x2000
	s_nop 0
	global_load_lds_dwordx4 v[218:219], off
	s_waitcnt vmcnt(8)
	s_waitcnt lgkmcnt(0)
	s_barrier
	s_setprio 1
	v_mfma_f32_16x16x32_bf16 v[42:45], v[144:147], v[160:163], v[42:45]
	v_mfma_f32_16x16x32_bf16 v[38:41], v[152:155], v[160:163], v[38:41]
	v_mfma_f32_16x16x32_bf16 v[34:37], v[144:147], v[168:171], v[34:37]
	v_mfma_f32_16x16x32_bf16 v[30:33], v[152:155], v[168:171], v[30:33]
	v_mfma_f32_16x16x32_bf16 v[26:29], v[144:147], v[176:179], v[26:29]
	v_mfma_f32_16x16x32_bf16 v[22:25], v[152:155], v[176:179], v[22:25]
	v_mfma_f32_16x16x32_bf16 v[18:21], v[144:147], v[184:187], v[18:21]
	v_mfma_f32_16x16x32_bf16 v[14:17], v[152:155], v[184:187], v[14:17]
	v_mfma_f32_16x16x32_bf16 v[42:45], v[148:151], v[164:167], v[42:45]
	v_mfma_f32_16x16x32_bf16 v[38:41], v[156:159], v[164:167], v[38:41]
	v_mfma_f32_16x16x32_bf16 v[34:37], v[148:151], v[172:175], v[34:37]
	v_mfma_f32_16x16x32_bf16 v[30:33], v[156:159], v[172:175], v[30:33]
	v_mfma_f32_16x16x32_bf16 v[26:29], v[148:151], v[180:183], v[26:29]
	v_mfma_f32_16x16x32_bf16 v[22:25], v[156:159], v[180:183], v[22:25]
	v_mfma_f32_16x16x32_bf16 v[18:21], v[148:151], v[188:191], v[18:21]
	v_mfma_f32_16x16x32_bf16 v[14:17], v[156:159], v[188:191], v[14:17]
	v_mfma_f32_16x16x32_bf16 v[10:13], v[192:195], v[160:163], v[10:13]
	v_mfma_f32_16x16x32_bf16 v[6:9], v[202:205], v[160:163], v[6:9]
	v_mfma_f32_16x16x32_bf16 v[2:5], v[192:195], v[168:171], v[2:5]
	v_mfma_f32_16x16x32_bf16 v[66:69], v[202:205], v[168:171], v[66:69]
	v_mfma_f32_16x16x32_bf16 v[70:73], v[192:195], v[176:179], v[70:73]
	v_mfma_f32_16x16x32_bf16 v[74:77], v[202:205], v[176:179], v[74:77]
	v_mfma_f32_16x16x32_bf16 v[82:85], v[192:195], v[184:187], v[82:85]
	v_mfma_f32_16x16x32_bf16 v[86:89], v[202:205], v[184:187], v[86:89]
	v_mfma_f32_16x16x32_bf16 v[10:13], v[198:201], v[164:167], v[10:13]
	v_mfma_f32_16x16x32_bf16 v[6:9], v[206:209], v[164:167], v[6:9]
	v_mfma_f32_16x16x32_bf16 v[2:5], v[198:201], v[172:175], v[2:5]
	v_mfma_f32_16x16x32_bf16 v[66:69], v[206:209], v[172:175], v[66:69]
	v_mfma_f32_16x16x32_bf16 v[70:73], v[198:201], v[180:183], v[70:73]
	v_mfma_f32_16x16x32_bf16 v[74:77], v[206:209], v[180:183], v[74:77]
	v_mfma_f32_16x16x32_bf16 v[82:85], v[198:201], v[188:191], v[82:85]
	v_mfma_f32_16x16x32_bf16 v[86:89], v[206:209], v[188:191], v[86:89]
	s_setprio 0
	s_add_i32 s41, 0, 0x18000
	s_barrier
	v_add_u32_e32 v156, 0x18000, v143
	ds_read_b128 v[144:147], v156
	ds_read_b128 v[148:151], v156 offset:1024
	ds_read_b128 v[152:155], v156 offset:2048
	ds_read_b128 v[156:159], v156 offset:3072
	ds_read_b128 v[160:163], v142 offset:32768
	ds_read_b128 v[164:167], v142 offset:33792
	ds_read_b128 v[168:171], v142 offset:34816
	ds_read_b128 v[172:175], v142 offset:35840
	ds_read_b128 v[176:179], v142 offset:36864
	ds_read_b128 v[180:183], v142 offset:37888
	ds_read_b128 v[184:187], v142 offset:38912
	ds_read_b128 v[188:191], v142 offset:39936
	s_mov_b32 m0, s79
	v_lshl_add_u64 v[192:193], v[210:211], 0, s[28:29]
	global_load_lds_dwordx4 v[192:193], off
	v_lshl_add_u64 v[192:193], v[212:213], 0, s[28:29]
	s_mov_b32 m0, s78
	s_nop 0
	global_load_lds_dwordx4 v[192:193], off
	v_add_u32_e32 v197, 0x1c000, v143
	ds_read_b128 v[192:195], v197
	ds_read_b128 v[198:201], v197 offset:1024
	ds_read_b128 v[202:205], v197 offset:2048
	ds_read_b128 v[206:209], v197 offset:3072
	s_waitcnt vmcnt(8)
	s_waitcnt lgkmcnt(0)
	s_barrier
	s_setprio 1
	v_mfma_f32_16x16x32_bf16 v[126:129], v[144:147], v[160:163], v[126:129]
	v_mfma_f32_16x16x32_bf16 v[122:125], v[152:155], v[160:163], v[122:125]
	v_mfma_f32_16x16x32_bf16 v[118:121], v[144:147], v[168:171], v[118:121]
	v_mfma_f32_16x16x32_bf16 v[114:117], v[152:155], v[168:171], v[114:117]
	v_mfma_f32_16x16x32_bf16 v[110:113], v[144:147], v[176:179], v[110:113]
	v_mfma_f32_16x16x32_bf16 v[106:109], v[152:155], v[176:179], v[106:109]
	v_mfma_f32_16x16x32_bf16 v[102:105], v[144:147], v[184:187], v[102:105]
	v_mfma_f32_16x16x32_bf16 v[98:101], v[152:155], v[184:187], v[98:101]
	v_mfma_f32_16x16x32_bf16 v[126:129], v[148:151], v[164:167], v[126:129]
	v_mfma_f32_16x16x32_bf16 v[122:125], v[156:159], v[164:167], v[122:125]
	v_mfma_f32_16x16x32_bf16 v[118:121], v[148:151], v[172:175], v[118:121]
	v_mfma_f32_16x16x32_bf16 v[114:117], v[156:159], v[172:175], v[114:117]
	v_mfma_f32_16x16x32_bf16 v[110:113], v[148:151], v[180:183], v[110:113]
	v_mfma_f32_16x16x32_bf16 v[106:109], v[156:159], v[180:183], v[106:109]
	v_mfma_f32_16x16x32_bf16 v[102:105], v[148:151], v[188:191], v[102:105]
	v_mfma_f32_16x16x32_bf16 v[98:101], v[156:159], v[188:191], v[98:101]
	v_mfma_f32_16x16x32_bf16 v[94:97], v[192:195], v[160:163], v[94:97]
	v_mfma_f32_16x16x32_bf16 v[90:93], v[202:205], v[160:163], v[90:93]
	v_mfma_f32_16x16x32_bf16 v[78:81], v[192:195], v[168:171], v[78:81]
	v_mfma_f32_16x16x32_bf16 v[62:65], v[202:205], v[168:171], v[62:65]
	v_mfma_f32_16x16x32_bf16 v[58:61], v[192:195], v[176:179], v[58:61]
	v_mfma_f32_16x16x32_bf16 v[54:57], v[202:205], v[176:179], v[54:57]
	v_mfma_f32_16x16x32_bf16 v[50:53], v[192:195], v[184:187], v[50:53]
	v_mfma_f32_16x16x32_bf16 v[46:49], v[202:205], v[184:187], v[46:49]
	v_mfma_f32_16x16x32_bf16 v[94:97], v[198:201], v[164:167], v[94:97]
	v_mfma_f32_16x16x32_bf16 v[90:93], v[206:209], v[164:167], v[90:93]
	v_mfma_f32_16x16x32_bf16 v[78:81], v[198:201], v[172:175], v[78:81]
	v_mfma_f32_16x16x32_bf16 v[62:65], v[206:209], v[172:175], v[62:65]
	v_mfma_f32_16x16x32_bf16 v[58:61], v[198:201], v[180:183], v[58:61]
	v_mfma_f32_16x16x32_bf16 v[54:57], v[206:209], v[180:183], v[54:57]
	v_mfma_f32_16x16x32_bf16 v[50:53], v[198:201], v[188:191], v[50:53]
	v_mfma_f32_16x16x32_bf16 v[46:49], v[206:209], v[188:191], v[46:49]
	s_setprio 0
	s_mov_b32 m0, s68
	v_lshl_add_u64 v[210:211], v[210:211], 0, s[34:35]
	s_barrier
	ds_read_b128 v[160:163], v142 offset:49152
	ds_read_b128 v[164:167], v142 offset:50176
	ds_read_b128 v[168:171], v142 offset:51200
	ds_read_b128 v[172:175], v142 offset:52224
	ds_read_b128 v[176:179], v142 offset:53248
	ds_read_b128 v[180:183], v142 offset:54272
	ds_read_b128 v[184:187], v142 offset:55296
	ds_read_b128 v[188:191], v142 offset:56320
	global_load_lds_dwordx4 v[210:211], off
	v_lshl_add_u64 v[210:211], v[212:213], 0, s[34:35]
	s_mov_b32 m0, s69
	s_nop 0
	global_load_lds_dwordx4 v[210:211], off
	s_add_i32 s44, 0, 0x1c000
	s_add_i32 s41, s41, s37
	v_lshl_add_u64 v[218:219], v[214:215], 0, s[30:31]
	s_mov_b32 m0, s41
	s_nop 0
	global_load_lds_dwordx4 v[218:219], off
	v_lshl_add_u64 v[218:219], v[216:217], 0, s[30:31]
	s_add_i32 m0, s41, 0x2000
	s_nop 0
	global_load_lds_dwordx4 v[218:219], off
	s_add_i32 s41, s44, s37
	v_lshl_add_u64 v[218:219], v[214:215], 0, s[92:93]
	s_mov_b32 m0, s41
	s_nop 0
	global_load_lds_dwordx4 v[218:219], off
	v_lshl_add_u64 v[218:219], v[216:217], 0, s[92:93]
	s_add_i32 m0, s41, 0x2000
	s_nop 0
	global_load_lds_dwordx4 v[218:219], off
	s_waitcnt vmcnt(8)
	s_waitcnt lgkmcnt(0)
	s_barrier
	s_setprio 1
	v_mfma_f32_16x16x32_bf16 v[42:45], v[144:147], v[160:163], v[42:45]
	v_mfma_f32_16x16x32_bf16 v[38:41], v[152:155], v[160:163], v[38:41]
	v_mfma_f32_16x16x32_bf16 v[34:37], v[144:147], v[168:171], v[34:37]
	v_mfma_f32_16x16x32_bf16 v[30:33], v[152:155], v[168:171], v[30:33]
	v_mfma_f32_16x16x32_bf16 v[26:29], v[144:147], v[176:179], v[26:29]
	v_mfma_f32_16x16x32_bf16 v[22:25], v[152:155], v[176:179], v[22:25]
	v_mfma_f32_16x16x32_bf16 v[18:21], v[144:147], v[184:187], v[18:21]
	v_mfma_f32_16x16x32_bf16 v[14:17], v[152:155], v[184:187], v[14:17]
	v_mfma_f32_16x16x32_bf16 v[42:45], v[148:151], v[164:167], v[42:45]
	v_mfma_f32_16x16x32_bf16 v[38:41], v[156:159], v[164:167], v[38:41]
	v_mfma_f32_16x16x32_bf16 v[34:37], v[148:151], v[172:175], v[34:37]
	v_mfma_f32_16x16x32_bf16 v[30:33], v[156:159], v[172:175], v[30:33]
	v_mfma_f32_16x16x32_bf16 v[26:29], v[148:151], v[180:183], v[26:29]
	v_mfma_f32_16x16x32_bf16 v[22:25], v[156:159], v[180:183], v[22:25]
	v_mfma_f32_16x16x32_bf16 v[18:21], v[148:151], v[188:191], v[18:21]
	v_mfma_f32_16x16x32_bf16 v[14:17], v[156:159], v[188:191], v[14:17]
	v_mfma_f32_16x16x32_bf16 v[10:13], v[192:195], v[160:163], v[10:13]
	v_mfma_f32_16x16x32_bf16 v[6:9], v[202:205], v[160:163], v[6:9]
	v_mfma_f32_16x16x32_bf16 v[2:5], v[192:195], v[168:171], v[2:5]
	v_mfma_f32_16x16x32_bf16 v[66:69], v[202:205], v[168:171], v[66:69]
	v_mfma_f32_16x16x32_bf16 v[70:73], v[192:195], v[176:179], v[70:73]
	v_mfma_f32_16x16x32_bf16 v[74:77], v[202:205], v[176:179], v[74:77]
	v_mfma_f32_16x16x32_bf16 v[82:85], v[192:195], v[184:187], v[82:85]
	v_mfma_f32_16x16x32_bf16 v[86:89], v[202:205], v[184:187], v[86:89]
	v_mfma_f32_16x16x32_bf16 v[10:13], v[198:201], v[164:167], v[10:13]
	v_mfma_f32_16x16x32_bf16 v[6:9], v[206:209], v[164:167], v[6:9]
	v_mfma_f32_16x16x32_bf16 v[2:5], v[198:201], v[172:175], v[2:5]
	v_mfma_f32_16x16x32_bf16 v[66:69], v[206:209], v[172:175], v[66:69]
	v_mfma_f32_16x16x32_bf16 v[70:73], v[198:201], v[180:183], v[70:73]
	v_mfma_f32_16x16x32_bf16 v[74:77], v[206:209], v[180:183], v[74:77]
	v_mfma_f32_16x16x32_bf16 v[82:85], v[198:201], v[188:191], v[82:85]
	v_mfma_f32_16x16x32_bf16 v[86:89], v[206:209], v[188:191], v[86:89]
	s_setprio 0
	s_add_i32 s16, s16, 2
	v_lshl_add_u64 v[134:135], v[134:135], 0, s[98:99]
	v_lshl_add_u64 v[136:137], v[136:137], 0, s[98:99]
	v_lshl_add_u64 v[138:139], v[138:139], 0, s[98:99]
	s_cmp_gt_u32 s16, 11
	v_lshl_add_u64 v[140:141], v[140:141], 0, s[98:99]
	s_barrier
	s_cbranch_scc0 .LBB0_161
	s_waitcnt vmcnt(6)
	s_add_u32 s0, s0, 0x40780
	v_add_u32_e32 v143, 0, v143
	s_addc_u32 s1, s1, 0
	s_mov_b32 m0, s40
	v_add_u32_e32 v148, 0x10000, v143
	v_lshl_add_u64 v[130:131], s[0:1], 0, v[130:131]
	ds_read_b128 v[134:137], v148
	ds_read_b128 v[138:141], v148 offset:1024
	ds_read_b128 v[144:147], v148 offset:2048
	ds_read_b128 v[148:151], v148 offset:3072
	ds_read_b128 v[152:155], v142
	ds_read_b128 v[156:159], v142 offset:1024
	ds_read_b128 v[160:163], v142 offset:2048
	ds_read_b128 v[164:167], v142 offset:3072
	ds_read_b128 v[168:171], v142 offset:4096
	ds_read_b128 v[172:175], v142 offset:5120
	ds_read_b128 v[176:179], v142 offset:6144
	ds_read_b128 v[180:183], v142 offset:7168
	global_load_lds_dwordx4 v[130:131], off
	v_lshl_add_u64 v[130:131], s[0:1], 0, v[132:133]
	s_mov_b32 m0, s17
	s_nop 0
	global_load_lds_dwordx4 v[130:131], off
	s_barrier
	s_waitcnt lgkmcnt(0)
	s_setprio 1
	s_waitcnt lgkmcnt(0)
	v_mfma_f32_16x16x32_bf16 v[126:129], v[134:137], v[152:155], v[126:129]
	v_mfma_f32_16x16x32_bf16 v[122:125], v[144:147], v[152:155], v[122:125]
	v_mfma_f32_16x16x32_bf16 v[118:121], v[134:137], v[160:163], v[118:121]
	v_mfma_f32_16x16x32_bf16 v[114:117], v[144:147], v[160:163], v[114:117]
	v_mfma_f32_16x16x32_bf16 v[110:113], v[134:137], v[168:171], v[110:113]
	v_mfma_f32_16x16x32_bf16 v[106:109], v[144:147], v[168:171], v[106:109]
	v_mfma_f32_16x16x32_bf16 v[102:105], v[134:137], v[176:179], v[102:105]
	v_mfma_f32_16x16x32_bf16 v[98:101], v[144:147], v[176:179], v[98:101]
	v_mfma_f32_16x16x32_bf16 v[126:129], v[138:141], v[156:159], v[126:129]
	v_mfma_f32_16x16x32_bf16 v[122:125], v[148:151], v[156:159], v[122:125]
	v_mfma_f32_16x16x32_bf16 v[118:121], v[138:141], v[164:167], v[118:121]
	v_mfma_f32_16x16x32_bf16 v[114:117], v[148:151], v[164:167], v[114:117]
	v_mfma_f32_16x16x32_bf16 v[110:113], v[138:141], v[172:175], v[110:113]
	v_mfma_f32_16x16x32_bf16 v[106:109], v[148:151], v[172:175], v[106:109]
	v_mfma_f32_16x16x32_bf16 v[102:105], v[138:141], v[180:183], v[102:105]
	v_mfma_f32_16x16x32_bf16 v[98:101], v[148:151], v[180:183], v[98:101]
	s_setprio 0
	v_add_u32_e32 v192, 0x14000, v143
	s_barrier
	ds_read_b128 v[130:133], v192
	ds_read_b128 v[184:187], v192 offset:1024
	ds_read_b128 v[188:191], v192 offset:2048
	ds_read_b128 v[192:195], v192 offset:3072
	s_barrier
	s_waitcnt lgkmcnt(0)
	s_setprio 1
	s_waitcnt lgkmcnt(0)
	v_mfma_f32_16x16x32_bf16 v[94:97], v[130:133], v[152:155], v[94:97]
	v_mfma_f32_16x16x32_bf16 v[90:93], v[188:191], v[152:155], v[90:93]
	v_mfma_f32_16x16x32_bf16 v[78:81], v[130:133], v[160:163], v[78:81]
	v_mfma_f32_16x16x32_bf16 v[94:97], v[184:187], v[156:159], v[94:97]
	v_mfma_f32_16x16x32_bf16 v[90:93], v[192:195], v[156:159], v[90:93]
	v_mfma_f32_16x16x32_bf16 v[78:81], v[184:187], v[164:167], v[78:81]
	v_mfma_f32_16x16x32_bf16 v[62:65], v[188:191], v[160:163], v[62:65]
	v_mfma_f32_16x16x32_bf16 v[58:61], v[130:133], v[168:171], v[58:61]
	v_mfma_f32_16x16x32_bf16 v[54:57], v[188:191], v[168:171], v[54:57]
	v_mfma_f32_16x16x32_bf16 v[50:53], v[130:133], v[176:179], v[50:53]
	v_mfma_f32_16x16x32_bf16 v[46:49], v[188:191], v[176:179], v[46:49]
	v_mfma_f32_16x16x32_bf16 v[62:65], v[192:195], v[164:167], v[62:65]
	v_mfma_f32_16x16x32_bf16 v[58:61], v[184:187], v[172:175], v[58:61]
	v_mfma_f32_16x16x32_bf16 v[54:57], v[192:195], v[172:175], v[54:57]
	v_mfma_f32_16x16x32_bf16 v[50:53], v[184:187], v[180:183], v[50:53]
	v_mfma_f32_16x16x32_bf16 v[46:49], v[192:195], v[180:183], v[46:49]
	s_setprio 0
	s_barrier
	ds_read_b128 v[152:155], v142 offset:16384
	ds_read_b128 v[156:159], v142 offset:17408
	ds_read_b128 v[160:163], v142 offset:18432
	ds_read_b128 v[164:167], v142 offset:19456
	ds_read_b128 v[168:171], v142 offset:20480
	ds_read_b128 v[172:175], v142 offset:21504
	ds_read_b128 v[176:179], v142 offset:22528
	ds_read_b128 v[180:183], v142 offset:23552
	s_waitcnt vmcnt(4)
	s_barrier
	s_waitcnt lgkmcnt(0)
	s_setprio 1
	s_waitcnt lgkmcnt(0)
	v_mfma_f32_16x16x32_bf16 v[42:45], v[134:137], v[152:155], v[42:45]
	v_mfma_f32_16x16x32_bf16 v[38:41], v[144:147], v[152:155], v[38:41]
	v_mfma_f32_16x16x32_bf16 v[34:37], v[134:137], v[160:163], v[34:37]
	v_mfma_f32_16x16x32_bf16 v[30:33], v[144:147], v[160:163], v[30:33]
	v_mfma_f32_16x16x32_bf16 v[26:29], v[134:137], v[168:171], v[26:29]
	v_mfma_f32_16x16x32_bf16 v[22:25], v[144:147], v[168:171], v[22:25]
	v_mfma_f32_16x16x32_bf16 v[18:21], v[134:137], v[176:179], v[18:21]
	v_mfma_f32_16x16x32_bf16 v[14:17], v[144:147], v[176:179], v[14:17]
	v_mfma_f32_16x16x32_bf16 v[42:45], v[138:141], v[156:159], v[42:45]
	v_mfma_f32_16x16x32_bf16 v[38:41], v[148:151], v[156:159], v[38:41]
	v_mfma_f32_16x16x32_bf16 v[34:37], v[138:141], v[164:167], v[34:37]
	v_mfma_f32_16x16x32_bf16 v[30:33], v[148:151], v[164:167], v[30:33]
	v_mfma_f32_16x16x32_bf16 v[26:29], v[138:141], v[172:175], v[26:29]
	v_mfma_f32_16x16x32_bf16 v[22:25], v[148:151], v[172:175], v[22:25]
	v_mfma_f32_16x16x32_bf16 v[18:21], v[138:141], v[180:183], v[18:21]
	v_mfma_f32_16x16x32_bf16 v[14:17], v[148:151], v[180:183], v[14:17]
	s_setprio 0
	s_setprio 1
	v_mfma_f32_16x16x32_bf16 v[70:73], v[130:133], v[168:171], v[70:73]
	v_mfma_f32_16x16x32_bf16 v[198:201], v[184:187], v[172:175], v[70:73]
	v_mfma_f32_16x16x32_bf16 v[70:73], v[188:191], v[168:171], v[74:77]
	v_mfma_f32_16x16x32_bf16 v[66:69], v[188:191], v[160:163], v[66:69]
	v_mfma_f32_16x16x32_bf16 v[74:77], v[192:195], v[172:175], v[70:73]
	v_mfma_f32_16x16x32_bf16 v[70:73], v[130:133], v[176:179], v[82:85]
	v_mfma_f32_16x16x32_bf16 v[10:13], v[130:133], v[152:155], v[10:13]
	v_mfma_f32_16x16x32_bf16 v[6:9], v[188:191], v[152:155], v[6:9]
	v_mfma_f32_16x16x32_bf16 v[2:5], v[130:133], v[160:163], v[2:5]
	v_mfma_f32_16x16x32_bf16 v[66:69], v[192:195], v[164:167], v[66:69]
	v_mfma_f32_16x16x32_bf16 v[202:205], v[184:187], v[180:183], v[70:73]
	v_mfma_f32_16x16x32_bf16 v[70:73], v[188:191], v[176:179], v[86:89]
	v_mfma_f32_16x16x32_bf16 v[10:13], v[184:187], v[156:159], v[10:13]
	v_mfma_f32_16x16x32_bf16 v[6:9], v[192:195], v[156:159], v[6:9]
	v_mfma_f32_16x16x32_bf16 v[2:5], v[184:187], v[164:167], v[2:5]
	v_mfma_f32_16x16x32_bf16 v[206:209], v[192:195], v[180:183], v[70:73]
	s_setprio 0
	v_add_u32_e32 v86, 0x18000, v143
	s_barrier
	s_nop 0
	ds_read_b128 v[70:73], v86
	ds_read_b128 v[82:85], v86 offset:1024
	ds_read_b128 v[134:137], v86 offset:2048
	ds_read_b128 v[210:213], v86 offset:3072
	ds_read_b128 v[86:89], v142 offset:32768
	ds_read_b128 v[130:133], v142 offset:33792
	ds_read_b128 v[138:141], v142 offset:34816
	ds_read_b128 v[154:157], v142 offset:35840
	ds_read_b128 v[214:217], v142 offset:36864
	ds_read_b128 v[218:221], v142 offset:37888
	ds_read_b128 v[226:229], v142 offset:38912
	ds_read_b128 v[230:233], v142 offset:39936
	s_waitcnt vmcnt(2)
	s_barrier
	s_waitcnt lgkmcnt(0)
	s_setprio 1
	s_waitcnt lgkmcnt(0)
	v_mfma_f32_16x16x32_bf16 v[126:129], v[70:73], v[86:89], v[126:129]
	v_mfma_f32_16x16x32_bf16 v[122:125], v[134:137], v[86:89], v[122:125]
	v_mfma_f32_16x16x32_bf16 v[118:121], v[70:73], v[138:141], v[118:121]
	v_mfma_f32_16x16x32_bf16 v[114:117], v[134:137], v[138:141], v[114:117]
	v_mfma_f32_16x16x32_bf16 v[110:113], v[70:73], v[214:217], v[110:113]
	v_mfma_f32_16x16x32_bf16 v[106:109], v[134:137], v[214:217], v[106:109]
	v_mfma_f32_16x16x32_bf16 v[102:105], v[70:73], v[226:229], v[102:105]
	v_mfma_f32_16x16x32_bf16 v[98:101], v[134:137], v[226:229], v[98:101]
	v_mfma_f32_16x16x32_bf16 v[182:185], v[82:85], v[130:133], v[126:129]
	v_mfma_f32_16x16x32_bf16 v[178:181], v[210:213], v[130:133], v[122:125]
	v_mfma_f32_16x16x32_bf16 v[166:169], v[82:85], v[154:157], v[118:121]
	v_mfma_f32_16x16x32_bf16 v[162:165], v[210:213], v[154:157], v[114:117]
	v_mfma_f32_16x16x32_bf16 v[150:153], v[82:85], v[218:221], v[110:113]
	v_mfma_f32_16x16x32_bf16 v[146:149], v[210:213], v[218:221], v[106:109]
	v_mfma_f32_16x16x32_bf16 v[122:125], v[82:85], v[230:233], v[102:105]
	v_mfma_f32_16x16x32_bf16 v[114:117], v[210:213], v[230:233], v[98:101]
	s_setprio 0
	s_nop 1
	v_add_u32_e32 v98, 0x1c000, v143
	s_barrier
	ds_read_b128 v[234:237], v98
	ds_read_b128 v[238:241], v98 offset:1024
	ds_read_b128 v[242:245], v98 offset:2048
	ds_read_b128 v[246:249], v98 offset:3072
	s_waitcnt vmcnt(0)
	s_barrier
	s_waitcnt lgkmcnt(0)
	s_setprio 1
	s_waitcnt lgkmcnt(0)
	v_mfma_f32_16x16x32_bf16 v[94:97], v[234:237], v[86:89], v[94:97]
	v_mfma_f32_16x16x32_bf16 v[86:89], v[242:245], v[86:89], v[90:93]
	v_mfma_f32_16x16x32_bf16 v[78:81], v[234:237], v[138:141], v[78:81]
	v_mfma_f32_16x16x32_bf16 v[62:65], v[242:245], v[138:141], v[62:65]
	v_mfma_f32_16x16x32_bf16 v[58:61], v[234:237], v[214:217], v[58:61]
	v_mfma_f32_16x16x32_bf16 v[54:57], v[242:245], v[214:217], v[54:57]
	v_mfma_f32_16x16x32_bf16 v[50:53], v[234:237], v[226:229], v[50:53]
	v_mfma_f32_16x16x32_bf16 v[46:49], v[242:245], v[226:229], v[46:49]
	v_mfma_f32_16x16x32_bf16 v[190:193], v[238:241], v[130:133], v[94:97]
	v_mfma_f32_16x16x32_bf16 v[186:189], v[246:249], v[130:133], v[86:89]
	v_mfma_f32_16x16x32_bf16 v[174:177], v[238:241], v[154:157], v[78:81]
	v_mfma_f32_16x16x32_bf16 v[170:173], v[246:249], v[154:157], v[62:65]
	v_mfma_f32_16x16x32_bf16 v[158:161], v[238:241], v[218:221], v[58:61]
	v_mfma_f32_16x16x32_bf16 v[154:157], v[246:249], v[218:221], v[54:57]
	v_mfma_f32_16x16x32_bf16 v[138:141], v[238:241], v[230:233], v[50:53]
	v_mfma_f32_16x16x32_bf16 v[130:133], v[246:249], v[230:233], v[46:49]
	s_setprio 0
	s_barrier
	s_nop 0
	ds_read_b128 v[46:49], v142 offset:49152
	ds_read_b128 v[50:53], v142 offset:50176
	ds_read_b128 v[54:57], v142 offset:51200
	ds_read_b128 v[58:61], v142 offset:52224
	ds_read_b128 v[62:65], v142 offset:53248
	ds_read_b128 v[214:217], v142 offset:54272
	ds_read_b128 v[218:221], v142 offset:55296
	ds_read_b128 v[226:229], v142 offset:56320
	s_barrier
	s_waitcnt lgkmcnt(0)
	s_setprio 1
	s_waitcnt lgkmcnt(0)
	v_mfma_f32_16x16x32_bf16 v[42:45], v[70:73], v[46:49], v[42:45]
	v_mfma_f32_16x16x32_bf16 v[38:41], v[134:137], v[46:49], v[38:41]
	v_mfma_f32_16x16x32_bf16 v[34:37], v[70:73], v[54:57], v[34:37]
	v_mfma_f32_16x16x32_bf16 v[30:33], v[134:137], v[54:57], v[30:33]
	v_mfma_f32_16x16x32_bf16 v[26:29], v[70:73], v[62:65], v[26:29]
	v_mfma_f32_16x16x32_bf16 v[22:25], v[134:137], v[62:65], v[22:25]
	v_mfma_f32_16x16x32_bf16 v[18:21], v[70:73], v[218:221], v[18:21]
	v_mfma_f32_16x16x32_bf16 v[14:17], v[134:137], v[218:221], v[14:17]
	v_mfma_f32_16x16x32_bf16 v[142:145], v[82:85], v[50:53], v[42:45]
	v_mfma_f32_16x16x32_bf16 v[126:129], v[210:213], v[50:53], v[38:41]
	v_mfma_f32_16x16x32_bf16 v[110:113], v[82:85], v[58:61], v[34:37]
	v_mfma_f32_16x16x32_bf16 v[102:105], v[210:213], v[58:61], v[30:33]
	v_mfma_f32_16x16x32_bf16 v[94:97], v[82:85], v[214:217], v[26:29]
	v_mfma_f32_16x16x32_bf16 v[86:89], v[210:213], v[214:217], v[22:25]
	v_mfma_f32_16x16x32_bf16 v[78:81], v[82:85], v[226:229], v[18:21]
	v_mfma_f32_16x16x32_bf16 v[70:73], v[210:213], v[226:229], v[14:17]
	s_setprio 0
	s_setprio 1
	v_mfma_f32_16x16x32_bf16 v[2:5], v[234:237], v[54:57], v[2:5]
	v_mfma_f32_16x16x32_bf16 v[106:109], v[238:241], v[58:61], v[2:5]
	v_mfma_f32_16x16x32_bf16 v[2:5], v[242:245], v[54:57], v[66:69]
	v_mfma_f32_16x16x32_bf16 v[98:101], v[246:249], v[58:61], v[2:5]
	v_mfma_f32_16x16x32_bf16 v[2:5], v[234:237], v[62:65], v[198:201]
	v_mfma_f32_16x16x32_bf16 v[90:93], v[238:241], v[214:217], v[2:5]
	v_mfma_f32_16x16x32_bf16 v[2:5], v[242:245], v[62:65], v[74:77]
	v_mfma_f32_16x16x32_bf16 v[82:85], v[246:249], v[214:217], v[2:5]
	v_mfma_f32_16x16x32_bf16 v[2:5], v[234:237], v[218:221], v[202:205]
	v_mfma_f32_16x16x32_bf16 v[10:13], v[234:237], v[46:49], v[10:13]
	v_mfma_f32_16x16x32_bf16 v[6:9], v[242:245], v[46:49], v[6:9]
	v_mfma_f32_16x16x32_bf16 v[74:77], v[238:241], v[226:229], v[2:5]
	v_mfma_f32_16x16x32_bf16 v[2:5], v[242:245], v[218:221], v[206:209]
	v_mfma_f32_16x16x32_bf16 v[134:137], v[238:241], v[50:53], v[10:13]
	v_mfma_f32_16x16x32_bf16 v[118:121], v[246:249], v[50:53], v[6:9]
	v_mfma_f32_16x16x32_bf16 v[66:69], v[246:249], v[226:229], v[2:5]
	s_setprio 0
	s_cmpk_lt_u32 s33, 0x100
	s_barrier
	s_cbranch_scc0 .LBB0_164
	s_barrier

.LBB0_196:
	v_add_u32_e32 v156, 0x10000, v143
	ds_read_b128 v[144:147], v156
	ds_read_b128 v[148:151], v156 offset:1024
	ds_read_b128 v[152:155], v156 offset:2048
	ds_read_b128 v[156:159], v156 offset:3072
	ds_read_b128 v[160:163], v142
	ds_read_b128 v[164:167], v142 offset:1024
	ds_read_b128 v[168:171], v142 offset:2048
	ds_read_b128 v[172:175], v142 offset:3072
	ds_read_b128 v[176:179], v142 offset:4096
	ds_read_b128 v[180:183], v142 offset:5120
	ds_read_b128 v[184:187], v142 offset:6144
	ds_read_b128 v[188:191], v142 offset:7168
	s_add_i32 s45, 0, 0x10000
	v_lshl_add_u64 v[210:211], v[138:139], 0, s[14:15]
	s_add_i32 s44, s69, 0xc000
	v_lshl_add_u64 v[192:193], v[210:211], 0, s[94:95]
	s_mov_b32 m0, s44
	v_lshl_add_u64 v[212:213], v[140:141], 0, s[14:15]
	s_add_i32 s41, s69, 0xe000
	global_load_lds_dwordx4 v[192:193], off
	v_lshl_add_u64 v[192:193], v[212:213], 0, s[94:95]
	s_mov_b32 m0, s41
	s_nop 0
	global_load_lds_dwordx4 v[192:193], off
	v_add_u32_e32 v197, 0x14000, v143
	ds_read_b128 v[192:195], v197
	ds_read_b128 v[198:201], v197 offset:1024
	ds_read_b128 v[202:205], v197 offset:2048
	ds_read_b128 v[206:209], v197 offset:3072
	s_waitcnt vmcnt(8)
	s_waitcnt lgkmcnt(0)
	s_barrier
	s_setprio 1
	v_mfma_f32_16x16x32_bf16 v[126:129], v[144:147], v[160:163], v[126:129]
	v_mfma_f32_16x16x32_bf16 v[122:125], v[152:155], v[160:163], v[122:125]
	v_mfma_f32_16x16x32_bf16 v[118:121], v[144:147], v[168:171], v[118:121]
	v_mfma_f32_16x16x32_bf16 v[114:117], v[152:155], v[168:171], v[114:117]
	v_mfma_f32_16x16x32_bf16 v[110:113], v[144:147], v[176:179], v[110:113]
	v_mfma_f32_16x16x32_bf16 v[106:109], v[152:155], v[176:179], v[106:109]
	v_mfma_f32_16x16x32_bf16 v[102:105], v[144:147], v[184:187], v[102:105]
	v_mfma_f32_16x16x32_bf16 v[98:101], v[152:155], v[184:187], v[98:101]
	v_mfma_f32_16x16x32_bf16 v[126:129], v[148:151], v[164:167], v[126:129]
	v_mfma_f32_16x16x32_bf16 v[122:125], v[156:159], v[164:167], v[122:125]
	v_mfma_f32_16x16x32_bf16 v[118:121], v[148:151], v[172:175], v[118:121]
	v_mfma_f32_16x16x32_bf16 v[114:117], v[156:159], v[172:175], v[114:117]
	v_mfma_f32_16x16x32_bf16 v[110:113], v[148:151], v[180:183], v[110:113]
	v_mfma_f32_16x16x32_bf16 v[106:109], v[156:159], v[180:183], v[106:109]
	v_mfma_f32_16x16x32_bf16 v[102:105], v[148:151], v[188:191], v[102:105]
	v_mfma_f32_16x16x32_bf16 v[98:101], v[156:159], v[188:191], v[98:101]
	v_mfma_f32_16x16x32_bf16 v[94:97], v[192:195], v[160:163], v[94:97]
	v_mfma_f32_16x16x32_bf16 v[90:93], v[202:205], v[160:163], v[90:93]
	v_mfma_f32_16x16x32_bf16 v[86:89], v[192:195], v[168:171], v[86:89]
	v_mfma_f32_16x16x32_bf16 v[82:85], v[202:205], v[168:171], v[82:85]
	v_mfma_f32_16x16x32_bf16 v[78:81], v[192:195], v[176:179], v[78:81]
	v_mfma_f32_16x16x32_bf16 v[70:73], v[202:205], v[176:179], v[70:73]
	v_mfma_f32_16x16x32_bf16 v[66:69], v[192:195], v[184:187], v[66:69]
	v_mfma_f32_16x16x32_bf16 v[62:65], v[202:205], v[184:187], v[62:65]
	v_mfma_f32_16x16x32_bf16 v[94:97], v[198:201], v[164:167], v[94:97]
	v_mfma_f32_16x16x32_bf16 v[90:93], v[206:209], v[164:167], v[90:93]
	v_mfma_f32_16x16x32_bf16 v[86:89], v[198:201], v[172:175], v[86:89]
	v_mfma_f32_16x16x32_bf16 v[82:85], v[206:209], v[172:175], v[82:85]
	v_mfma_f32_16x16x32_bf16 v[78:81], v[198:201], v[180:183], v[78:81]
	v_mfma_f32_16x16x32_bf16 v[70:73], v[206:209], v[180:183], v[70:73]
	v_mfma_f32_16x16x32_bf16 v[66:69], v[198:201], v[188:191], v[66:69]
	v_mfma_f32_16x16x32_bf16 v[62:65], v[206:209], v[188:191], v[62:65]
	s_setprio 0
	s_mov_b32 m0, s69
	v_lshl_add_u64 v[218:219], v[210:211], 0, s[38:39]
	s_barrier
	ds_read_b128 v[160:163], v142 offset:16384
	ds_read_b128 v[164:167], v142 offset:17408
	ds_read_b128 v[168:171], v142 offset:18432
	ds_read_b128 v[172:175], v142 offset:19456
	ds_read_b128 v[176:179], v142 offset:20480
	ds_read_b128 v[180:183], v142 offset:21504
	ds_read_b128 v[184:187], v142 offset:22528
	ds_read_b128 v[188:191], v142 offset:23552
	global_load_lds_dwordx4 v[218:219], off
	v_lshl_add_u64 v[218:219], v[212:213], 0, s[38:39]
	s_mov_b32 m0, s73
	s_nop 0
	global_load_lds_dwordx4 v[218:219], off
	s_add_i32 s75, 0, 0x14000
	v_lshl_add_u64 v[214:215], v[134:135], 0, s[14:15]
	s_add_i32 s45, s45, s68
	v_lshl_add_u64 v[216:217], v[214:215], 0, s[96:97]
	s_mov_b32 m0, s45
	s_nop 0
	global_load_lds_dwordx4 v[216:217], off
	v_lshl_add_u64 v[216:217], v[136:137], 0, s[14:15]
	v_lshl_add_u64 v[218:219], v[216:217], 0, s[96:97]
	s_add_i32 m0, s45, 0x2000
	s_nop 0
	global_load_lds_dwordx4 v[218:219], off
	s_add_i32 s45, s75, s68
	v_lshl_add_u64 v[218:219], v[214:215], 0, s[50:51]
	s_mov_b32 m0, s45
	s_nop 0
	global_load_lds_dwordx4 v[218:219], off
	v_lshl_add_u64 v[218:219], v[216:217], 0, s[50:51]
	s_add_i32 m0, s45, 0x2000
	s_nop 0
	global_load_lds_dwordx4 v[218:219], off
	s_waitcnt vmcnt(8)
	s_waitcnt lgkmcnt(0)
	s_barrier
	s_setprio 1
	v_mfma_f32_16x16x32_bf16 v[58:61], v[144:147], v[160:163], v[58:61]
	v_mfma_f32_16x16x32_bf16 v[54:57], v[152:155], v[160:163], v[54:57]
	v_mfma_f32_16x16x32_bf16 v[50:53], v[144:147], v[168:171], v[50:53]
	v_mfma_f32_16x16x32_bf16 v[46:49], v[152:155], v[168:171], v[46:49]
	v_mfma_f32_16x16x32_bf16 v[42:45], v[144:147], v[176:179], v[42:45]
	v_mfma_f32_16x16x32_bf16 v[38:41], v[152:155], v[176:179], v[38:41]
	v_mfma_f32_16x16x32_bf16 v[34:37], v[144:147], v[184:187], v[34:37]
	v_mfma_f32_16x16x32_bf16 v[30:33], v[152:155], v[184:187], v[30:33]
	v_mfma_f32_16x16x32_bf16 v[58:61], v[148:151], v[164:167], v[58:61]
	v_mfma_f32_16x16x32_bf16 v[54:57], v[156:159], v[164:167], v[54:57]
	v_mfma_f32_16x16x32_bf16 v[50:53], v[148:151], v[172:175], v[50:53]
	v_mfma_f32_16x16x32_bf16 v[46:49], v[156:159], v[172:175], v[46:49]
	v_mfma_f32_16x16x32_bf16 v[42:45], v[148:151], v[180:183], v[42:45]
	v_mfma_f32_16x16x32_bf16 v[38:41], v[156:159], v[180:183], v[38:41]
	v_mfma_f32_16x16x32_bf16 v[34:37], v[148:151], v[188:191], v[34:37]
	v_mfma_f32_16x16x32_bf16 v[30:33], v[156:159], v[188:191], v[30:33]
	v_mfma_f32_16x16x32_bf16 v[26:29], v[192:195], v[160:163], v[26:29]
	v_mfma_f32_16x16x32_bf16 v[22:25], v[202:205], v[160:163], v[22:25]
	v_mfma_f32_16x16x32_bf16 v[18:21], v[192:195], v[168:171], v[18:21]
	v_mfma_f32_16x16x32_bf16 v[14:17], v[202:205], v[168:171], v[14:17]
	v_mfma_f32_16x16x32_bf16 v[10:13], v[192:195], v[176:179], v[10:13]
	v_mfma_f32_16x16x32_bf16 v[6:9], v[202:205], v[176:179], v[6:9]
	v_mfma_f32_16x16x32_bf16 v[2:5], v[192:195], v[184:187], v[2:5]
	v_mfma_f32_16x16x32_bf16 v[74:77], v[202:205], v[184:187], v[74:77]
	v_mfma_f32_16x16x32_bf16 v[26:29], v[198:201], v[164:167], v[26:29]
	v_mfma_f32_16x16x32_bf16 v[22:25], v[206:209], v[164:167], v[22:25]
	v_mfma_f32_16x16x32_bf16 v[18:21], v[198:201], v[172:175], v[18:21]
	v_mfma_f32_16x16x32_bf16 v[14:17], v[206:209], v[172:175], v[14:17]
	v_mfma_f32_16x16x32_bf16 v[10:13], v[198:201], v[180:183], v[10:13]
	v_mfma_f32_16x16x32_bf16 v[6:9], v[206:209], v[180:183], v[6:9]
	v_mfma_f32_16x16x32_bf16 v[2:5], v[198:201], v[188:191], v[2:5]
	v_mfma_f32_16x16x32_bf16 v[74:77], v[206:209], v[188:191], v[74:77]
	s_setprio 0
	s_add_i32 s45, 0, 0x18000
	s_barrier
	v_add_u32_e32 v156, 0x18000, v143
	ds_read_b128 v[144:147], v156
	ds_read_b128 v[148:151], v156 offset:1024
	ds_read_b128 v[152:155], v156 offset:2048
	ds_read_b128 v[156:159], v156 offset:3072
	ds_read_b128 v[160:163], v142 offset:32768
	ds_read_b128 v[164:167], v142 offset:33792
	ds_read_b128 v[168:171], v142 offset:34816
	ds_read_b128 v[172:175], v142 offset:35840
	ds_read_b128 v[176:179], v142 offset:36864
	ds_read_b128 v[180:183], v142 offset:37888
	ds_read_b128 v[184:187], v142 offset:38912
	ds_read_b128 v[188:191], v142 offset:39936
	s_mov_b32 m0, s78
	v_lshl_add_u64 v[192:193], v[210:211], 0, s[4:5]
	global_load_lds_dwordx4 v[192:193], off
	v_lshl_add_u64 v[192:193], v[212:213], 0, s[4:5]
	s_mov_b32 m0, s74
	s_nop 0
	global_load_lds_dwordx4 v[192:193], off
	v_add_u32_e32 v197, 0x1c000, v143
	ds_read_b128 v[192:195], v197
	ds_read_b128 v[198:201], v197 offset:1024
	ds_read_b128 v[202:205], v197 offset:2048
	ds_read_b128 v[206:209], v197 offset:3072
	s_waitcnt vmcnt(8)
	s_waitcnt lgkmcnt(0)
	s_barrier
	s_setprio 1
	v_mfma_f32_16x16x32_bf16 v[126:129], v[144:147], v[160:163], v[126:129]
	v_mfma_f32_16x16x32_bf16 v[122:125], v[152:155], v[160:163], v[122:125]
	v_mfma_f32_16x16x32_bf16 v[118:121], v[144:147], v[168:171], v[118:121]
	v_mfma_f32_16x16x32_bf16 v[114:117], v[152:155], v[168:171], v[114:117]
	v_mfma_f32_16x16x32_bf16 v[110:113], v[144:147], v[176:179], v[110:113]
	v_mfma_f32_16x16x32_bf16 v[106:109], v[152:155], v[176:179], v[106:109]
	v_mfma_f32_16x16x32_bf16 v[102:105], v[144:147], v[184:187], v[102:105]
	v_mfma_f32_16x16x32_bf16 v[98:101], v[152:155], v[184:187], v[98:101]
	v_mfma_f32_16x16x32_bf16 v[126:129], v[148:151], v[164:167], v[126:129]
	v_mfma_f32_16x16x32_bf16 v[122:125], v[156:159], v[164:167], v[122:125]
	v_mfma_f32_16x16x32_bf16 v[118:121], v[148:151], v[172:175], v[118:121]
	v_mfma_f32_16x16x32_bf16 v[114:117], v[156:159], v[172:175], v[114:117]
	v_mfma_f32_16x16x32_bf16 v[110:113], v[148:151], v[180:183], v[110:113]
	v_mfma_f32_16x16x32_bf16 v[106:109], v[156:159], v[180:183], v[106:109]
	v_mfma_f32_16x16x32_bf16 v[102:105], v[148:151], v[188:191], v[102:105]
	v_mfma_f32_16x16x32_bf16 v[98:101], v[156:159], v[188:191], v[98:101]
	v_mfma_f32_16x16x32_bf16 v[94:97], v[192:195], v[160:163], v[94:97]
	v_mfma_f32_16x16x32_bf16 v[90:93], v[202:205], v[160:163], v[90:93]
	v_mfma_f32_16x16x32_bf16 v[86:89], v[192:195], v[168:171], v[86:89]
	v_mfma_f32_16x16x32_bf16 v[82:85], v[202:205], v[168:171], v[82:85]
	v_mfma_f32_16x16x32_bf16 v[78:81], v[192:195], v[176:179], v[78:81]
	v_mfma_f32_16x16x32_bf16 v[70:73], v[202:205], v[176:179], v[70:73]
	v_mfma_f32_16x16x32_bf16 v[66:69], v[192:195], v[184:187], v[66:69]
	v_mfma_f32_16x16x32_bf16 v[62:65], v[202:205], v[184:187], v[62:65]
	v_mfma_f32_16x16x32_bf16 v[94:97], v[198:201], v[164:167], v[94:97]
	v_mfma_f32_16x16x32_bf16 v[90:93], v[206:209], v[164:167], v[90:93]
	v_mfma_f32_16x16x32_bf16 v[86:89], v[198:201], v[172:175], v[86:89]
	v_mfma_f32_16x16x32_bf16 v[82:85], v[206:209], v[172:175], v[82:85]
	v_mfma_f32_16x16x32_bf16 v[78:81], v[198:201], v[180:183], v[78:81]
	v_mfma_f32_16x16x32_bf16 v[70:73], v[206:209], v[180:183], v[70:73]
	v_mfma_f32_16x16x32_bf16 v[66:69], v[198:201], v[188:191], v[66:69]
	v_mfma_f32_16x16x32_bf16 v[62:65], v[206:209], v[188:191], v[62:65]
	s_setprio 0
	s_mov_b32 m0, s36
	v_lshl_add_u64 v[210:211], v[210:211], 0, s[8:9]
	s_barrier
	ds_read_b128 v[160:163], v142 offset:49152
	ds_read_b128 v[164:167], v142 offset:50176
	ds_read_b128 v[168:171], v142 offset:51200
	ds_read_b128 v[172:175], v142 offset:52224
	ds_read_b128 v[176:179], v142 offset:53248
	ds_read_b128 v[180:183], v142 offset:54272
	ds_read_b128 v[184:187], v142 offset:55296
	ds_read_b128 v[188:191], v142 offset:56320
	global_load_lds_dwordx4 v[210:211], off
	v_lshl_add_u64 v[210:211], v[212:213], 0, s[8:9]
	s_mov_b32 m0, s37
	s_nop 0
	global_load_lds_dwordx4 v[210:211], off
	s_add_i32 s75, 0, 0x1c000
	s_add_i32 s45, s45, s68
	v_lshl_add_u64 v[218:219], v[214:215], 0, s[6:7]
	s_mov_b32 m0, s45
	s_nop 0
	global_load_lds_dwordx4 v[218:219], off
	v_lshl_add_u64 v[218:219], v[216:217], 0, s[6:7]
	s_add_i32 m0, s45, 0x2000
	s_nop 0
	global_load_lds_dwordx4 v[218:219], off
	s_add_i32 s45, s75, s68
	v_lshl_add_u64 v[218:219], v[214:215], 0, s[10:11]
	s_mov_b32 m0, s45
	s_nop 0
	global_load_lds_dwordx4 v[218:219], off
	v_lshl_add_u64 v[218:219], v[216:217], 0, s[10:11]
	s_add_i32 m0, s45, 0x2000
	s_nop 0
	global_load_lds_dwordx4 v[218:219], off
	s_waitcnt vmcnt(8)
	s_waitcnt lgkmcnt(0)
	s_barrier
	s_setprio 1
	v_mfma_f32_16x16x32_bf16 v[58:61], v[144:147], v[160:163], v[58:61]
	v_mfma_f32_16x16x32_bf16 v[54:57], v[152:155], v[160:163], v[54:57]
	v_mfma_f32_16x16x32_bf16 v[50:53], v[144:147], v[168:171], v[50:53]
	v_mfma_f32_16x16x32_bf16 v[46:49], v[152:155], v[168:171], v[46:49]
	v_mfma_f32_16x16x32_bf16 v[42:45], v[144:147], v[176:179], v[42:45]
	v_mfma_f32_16x16x32_bf16 v[38:41], v[152:155], v[176:179], v[38:41]
	v_mfma_f32_16x16x32_bf16 v[34:37], v[144:147], v[184:187], v[34:37]
	v_mfma_f32_16x16x32_bf16 v[30:33], v[152:155], v[184:187], v[30:33]
	v_mfma_f32_16x16x32_bf16 v[58:61], v[148:151], v[164:167], v[58:61]
	v_mfma_f32_16x16x32_bf16 v[54:57], v[156:159], v[164:167], v[54:57]
	v_mfma_f32_16x16x32_bf16 v[50:53], v[148:151], v[172:175], v[50:53]
	v_mfma_f32_16x16x32_bf16 v[46:49], v[156:159], v[172:175], v[46:49]
	v_mfma_f32_16x16x32_bf16 v[42:45], v[148:151], v[180:183], v[42:45]
	v_mfma_f32_16x16x32_bf16 v[38:41], v[156:159], v[180:183], v[38:41]
	v_mfma_f32_16x16x32_bf16 v[34:37], v[148:151], v[188:191], v[34:37]
	v_mfma_f32_16x16x32_bf16 v[30:33], v[156:159], v[188:191], v[30:33]
	v_mfma_f32_16x16x32_bf16 v[26:29], v[192:195], v[160:163], v[26:29]
	v_mfma_f32_16x16x32_bf16 v[22:25], v[202:205], v[160:163], v[22:25]
	v_mfma_f32_16x16x32_bf16 v[18:21], v[192:195], v[168:171], v[18:21]
	v_mfma_f32_16x16x32_bf16 v[14:17], v[202:205], v[168:171], v[14:17]
	v_mfma_f32_16x16x32_bf16 v[10:13], v[192:195], v[176:179], v[10:13]
	v_mfma_f32_16x16x32_bf16 v[6:9], v[202:205], v[176:179], v[6:9]
	v_mfma_f32_16x16x32_bf16 v[2:5], v[192:195], v[184:187], v[2:5]
	v_mfma_f32_16x16x32_bf16 v[74:77], v[202:205], v[184:187], v[74:77]
	v_mfma_f32_16x16x32_bf16 v[26:29], v[198:201], v[164:167], v[26:29]
	v_mfma_f32_16x16x32_bf16 v[22:25], v[206:209], v[164:167], v[22:25]
	v_mfma_f32_16x16x32_bf16 v[18:21], v[198:201], v[172:175], v[18:21]
	v_mfma_f32_16x16x32_bf16 v[14:17], v[206:209], v[172:175], v[14:17]
	v_mfma_f32_16x16x32_bf16 v[10:13], v[198:201], v[180:183], v[10:13]
	v_mfma_f32_16x16x32_bf16 v[6:9], v[206:209], v[180:183], v[6:9]
	v_mfma_f32_16x16x32_bf16 v[2:5], v[198:201], v[188:191], v[2:5]
	v_mfma_f32_16x16x32_bf16 v[74:77], v[206:209], v[188:191], v[74:77]
	s_setprio 0
	s_add_i32 s40, s40, 2
	v_lshl_add_u64 v[134:135], v[134:135], 0, s[98:99]
	v_lshl_add_u64 v[136:137], v[136:137], 0, s[98:99]
	v_lshl_add_u64 v[138:139], v[138:139], 0, s[98:99]
	s_cmp_gt_u32 s40, 11
	v_lshl_add_u64 v[140:141], v[140:141], 0, s[98:99]
	s_barrier
	s_cbranch_scc0 .LBB0_196
	s_waitcnt vmcnt(6)
	s_add_u32 s16, s16, 0x40780
	v_add_u32_e32 v143, 0, v143
	s_addc_u32 s17, s17, 0
	s_mov_b32 m0, s44
	v_add_u32_e32 v148, 0x10000, v143
	v_lshl_add_u64 v[130:131], s[16:17], 0, v[130:131]
	ds_read_b128 v[134:137], v148
	ds_read_b128 v[138:141], v148 offset:1024
	ds_read_b128 v[144:147], v148 offset:2048
	ds_read_b128 v[148:151], v148 offset:3072
	ds_read_b128 v[152:155], v142
	ds_read_b128 v[156:159], v142 offset:1024
	ds_read_b128 v[160:163], v142 offset:2048
	ds_read_b128 v[164:167], v142 offset:3072
	ds_read_b128 v[168:171], v142 offset:4096
	ds_read_b128 v[172:175], v142 offset:5120
	ds_read_b128 v[176:179], v142 offset:6144
	ds_read_b128 v[180:183], v142 offset:7168
	global_load_lds_dwordx4 v[130:131], off
	v_lshl_add_u64 v[130:131], s[16:17], 0, v[132:133]
	s_mov_b32 m0, s41
	s_nop 0
	global_load_lds_dwordx4 v[130:131], off
	s_barrier
	s_waitcnt lgkmcnt(0)
	s_setprio 1
	s_waitcnt lgkmcnt(0)
	v_mfma_f32_16x16x32_bf16 v[126:129], v[134:137], v[152:155], v[126:129]
	v_mfma_f32_16x16x32_bf16 v[122:125], v[144:147], v[152:155], v[122:125]
	v_mfma_f32_16x16x32_bf16 v[118:121], v[134:137], v[160:163], v[118:121]
	v_mfma_f32_16x16x32_bf16 v[114:117], v[144:147], v[160:163], v[114:117]
	v_mfma_f32_16x16x32_bf16 v[110:113], v[134:137], v[168:171], v[110:113]
	v_mfma_f32_16x16x32_bf16 v[106:109], v[144:147], v[168:171], v[106:109]
	v_mfma_f32_16x16x32_bf16 v[102:105], v[134:137], v[176:179], v[102:105]
	v_mfma_f32_16x16x32_bf16 v[126:129], v[138:141], v[156:159], v[126:129]
	v_mfma_f32_16x16x32_bf16 v[122:125], v[148:151], v[156:159], v[122:125]
	v_mfma_f32_16x16x32_bf16 v[118:121], v[138:141], v[164:167], v[118:121]
	v_mfma_f32_16x16x32_bf16 v[114:117], v[148:151], v[164:167], v[114:117]
	v_mfma_f32_16x16x32_bf16 v[110:113], v[138:141], v[172:175], v[110:113]
	v_mfma_f32_16x16x32_bf16 v[106:109], v[148:151], v[172:175], v[106:109]
	v_mfma_f32_16x16x32_bf16 v[102:105], v[138:141], v[180:183], v[102:105]
	v_mfma_f32_16x16x32_bf16 v[98:101], v[144:147], v[176:179], v[98:101]
	v_mfma_f32_16x16x32_bf16 v[98:101], v[148:151], v[180:183], v[98:101]
	s_setprio 0
	v_add_u32_e32 v192, 0x14000, v143
	s_barrier
	ds_read_b128 v[130:133], v192
	ds_read_b128 v[184:187], v192 offset:1024
	ds_read_b128 v[188:191], v192 offset:2048
	ds_read_b128 v[192:195], v192 offset:3072
	s_barrier
	s_waitcnt lgkmcnt(0)
	s_setprio 1
	s_waitcnt lgkmcnt(0)
	v_mfma_f32_16x16x32_bf16 v[94:97], v[130:133], v[152:155], v[94:97]
	v_mfma_f32_16x16x32_bf16 v[90:93], v[188:191], v[152:155], v[90:93]
	v_mfma_f32_16x16x32_bf16 v[82:85], v[188:191], v[160:163], v[82:85]
	v_mfma_f32_16x16x32_bf16 v[70:73], v[188:191], v[168:171], v[70:73]
	v_mfma_f32_16x16x32_bf16 v[66:69], v[130:133], v[176:179], v[66:69]
	v_mfma_f32_16x16x32_bf16 v[94:97], v[184:187], v[156:159], v[94:97]
	v_mfma_f32_16x16x32_bf16 v[90:93], v[192:195], v[156:159], v[90:93]
	v_mfma_f32_16x16x32_bf16 v[86:89], v[130:133], v[160:163], v[86:89]
	v_mfma_f32_16x16x32_bf16 v[82:85], v[192:195], v[164:167], v[82:85]
	v_mfma_f32_16x16x32_bf16 v[78:81], v[130:133], v[168:171], v[78:81]
	v_mfma_f32_16x16x32_bf16 v[152:155], v[192:195], v[172:175], v[70:73]
	v_mfma_f32_16x16x32_bf16 v[156:159], v[184:187], v[180:183], v[66:69]
	v_mfma_f32_16x16x32_bf16 v[62:65], v[188:191], v[176:179], v[62:65]
	v_mfma_f32_16x16x32_bf16 v[86:89], v[184:187], v[164:167], v[86:89]
	v_mfma_f32_16x16x32_bf16 v[78:81], v[184:187], v[172:175], v[78:81]
	v_mfma_f32_16x16x32_bf16 v[160:163], v[192:195], v[180:183], v[62:65]
	s_setprio 0
	s_barrier
	s_nop 2
	ds_read_b128 v[62:65], v142 offset:16384
	ds_read_b128 v[66:69], v142 offset:17408
	ds_read_b128 v[70:73], v142 offset:18432
	ds_read_b128 v[164:167], v142 offset:19456
	ds_read_b128 v[168:171], v142 offset:20480
	ds_read_b128 v[172:175], v142 offset:21504
	ds_read_b128 v[176:179], v142 offset:22528
	ds_read_b128 v[180:183], v142 offset:23552
	s_waitcnt vmcnt(4)
	s_barrier
	s_waitcnt lgkmcnt(0)
	s_setprio 1
	s_waitcnt lgkmcnt(0)
	v_mfma_f32_16x16x32_bf16 v[58:61], v[134:137], v[62:65], v[58:61]
	v_mfma_f32_16x16x32_bf16 v[50:53], v[134:137], v[70:73], v[50:53]
	v_mfma_f32_16x16x32_bf16 v[42:45], v[134:137], v[168:171], v[42:45]
	v_mfma_f32_16x16x32_bf16 v[34:37], v[134:137], v[176:179], v[34:37]
	v_mfma_f32_16x16x32_bf16 v[30:33], v[144:147], v[176:179], v[30:33]
	v_mfma_f32_16x16x32_bf16 v[202:205], v[138:141], v[66:69], v[58:61]
	v_mfma_f32_16x16x32_bf16 v[54:57], v[144:147], v[62:65], v[54:57]
	v_mfma_f32_16x16x32_bf16 v[50:53], v[138:141], v[164:167], v[50:53]
	v_mfma_f32_16x16x32_bf16 v[46:49], v[144:147], v[70:73], v[46:49]
	v_mfma_f32_16x16x32_bf16 v[214:217], v[138:141], v[172:175], v[42:45]
	v_mfma_f32_16x16x32_bf16 v[38:41], v[144:147], v[168:171], v[38:41]
	v_mfma_f32_16x16x32_bf16 v[138:141], v[138:141], v[180:183], v[34:37]
	v_mfma_f32_16x16x32_bf16 v[144:147], v[148:151], v[180:183], v[30:33]
	v_mfma_f32_16x16x32_bf16 v[206:209], v[148:151], v[66:69], v[54:57]
	v_mfma_f32_16x16x32_bf16 v[210:213], v[148:151], v[164:167], v[46:49]
	v_mfma_f32_16x16x32_bf16 v[218:221], v[148:151], v[172:175], v[38:41]
	s_setprio 0
	s_setprio 1
	v_mfma_f32_16x16x32_bf16 v[26:29], v[130:133], v[62:65], v[26:29]
	v_mfma_f32_16x16x32_bf16 v[10:13], v[130:133], v[168:171], v[10:13]
	v_mfma_f32_16x16x32_bf16 v[6:9], v[188:191], v[168:171], v[6:9]
	v_mfma_f32_16x16x32_bf16 v[2:5], v[130:133], v[176:179], v[2:5]
	v_mfma_f32_16x16x32_bf16 v[148:151], v[184:187], v[66:69], v[26:29]
	v_mfma_f32_16x16x32_bf16 v[22:25], v[188:191], v[62:65], v[22:25]
	v_mfma_f32_16x16x32_bf16 v[18:21], v[130:133], v[70:73], v[18:21]
	v_mfma_f32_16x16x32_bf16 v[14:17], v[188:191], v[70:73], v[14:17]
	v_mfma_f32_16x16x32_bf16 v[238:241], v[184:187], v[172:175], v[10:13]
	v_mfma_f32_16x16x32_bf16 v[168:171], v[192:195], v[172:175], v[6:9]
	v_mfma_f32_16x16x32_bf16 v[172:175], v[184:187], v[180:183], v[2:5]
	v_mfma_f32_16x16x32_bf16 v[2:5], v[188:191], v[176:179], v[74:77]
	v_mfma_f32_16x16x32_bf16 v[230:233], v[192:195], v[66:69], v[22:25]
	v_mfma_f32_16x16x32_bf16 v[234:237], v[184:187], v[164:167], v[18:21]
	v_mfma_f32_16x16x32_bf16 v[164:167], v[192:195], v[164:167], v[14:17]
	v_mfma_f32_16x16x32_bf16 v[176:179], v[192:195], v[180:183], v[2:5]
	s_setprio 0
	v_add_u32_e32 v6, 0x18000, v143
	s_barrier
	s_nop 0
	ds_read_b128 v[2:5], v6
	ds_read_b128 v[72:75], v6 offset:1024
	ds_read_b128 v[180:183], v6 offset:2048
	ds_read_b128 v[184:187], v6 offset:3072
	ds_read_b128 v[6:9], v142 offset:32768
	ds_read_b128 v[14:17], v142 offset:33792
	ds_read_b128 v[18:21], v142 offset:34816
	ds_read_b128 v[28:31], v142 offset:35840
	ds_read_b128 v[188:191], v142 offset:36864
	ds_read_b128 v[192:195], v142 offset:37888
	ds_read_b128 v[242:245], v142 offset:38912
	ds_read_b128 v[246:249], v142 offset:39936
	s_waitcnt vmcnt(2)
	s_barrier
	s_waitcnt lgkmcnt(0)
	s_setprio 1
	s_waitcnt lgkmcnt(0)
	v_mfma_f32_16x16x32_bf16 v[10:13], v[2:5], v[6:9], v[126:129]
	v_mfma_f32_16x16x32_bf16 v[56:59], v[72:75], v[14:17], v[10:13]
	v_mfma_f32_16x16x32_bf16 v[10:13], v[180:183], v[6:9], v[122:125]
	v_mfma_f32_16x16x32_bf16 v[68:71], v[184:187], v[14:17], v[10:13]
	v_mfma_f32_16x16x32_bf16 v[10:13], v[2:5], v[18:21], v[118:121]
	v_mfma_f32_16x16x32_bf16 v[38:41], v[72:75], v[28:31], v[10:13]
	v_mfma_f32_16x16x32_bf16 v[10:13], v[180:183], v[18:21], v[114:117]
	v_mfma_f32_16x16x32_bf16 v[60:63], v[184:187], v[28:31], v[10:13]
	v_mfma_f32_16x16x32_bf16 v[10:13], v[2:5], v[188:191], v[110:113]
	v_mfma_f32_16x16x32_bf16 v[24:27], v[72:75], v[192:195], v[10:13]
	v_mfma_f32_16x16x32_bf16 v[10:13], v[180:183], v[188:191], v[106:109]
	v_mfma_f32_16x16x32_bf16 v[42:45], v[184:187], v[192:195], v[10:13]
	v_mfma_f32_16x16x32_bf16 v[10:13], v[2:5], v[242:245], v[102:105]
	v_mfma_f32_16x16x32_bf16 v[32:35], v[180:183], v[242:245], v[98:101]
	v_mfma_f32_16x16x32_bf16 v[10:13], v[72:75], v[246:249], v[10:13]
	v_mfma_f32_16x16x32_bf16 v[34:37], v[184:187], v[246:249], v[32:35]
	s_setprio 0
	v_add_u32_e32 v22, 0x1c000, v143
	s_barrier
	ds_read_b128 v[98:101], v22
	ds_read_b128 v[102:105], v22 offset:1024
	ds_read_b128 v[226:229], v22 offset:2048
	ds_read_b128 v[198:201], v22 offset:3072
	s_waitcnt vmcnt(0)
	s_barrier
	s_waitcnt lgkmcnt(0)
	s_setprio 1
	s_waitcnt lgkmcnt(0)
	v_mfma_f32_16x16x32_bf16 v[46:49], v[98:101], v[6:9], v[94:97]
	v_mfma_f32_16x16x32_bf16 v[6:9], v[226:229], v[6:9], v[90:93]
	v_mfma_f32_16x16x32_bf16 v[130:133], v[198:201], v[14:17], v[6:9]
	v_mfma_f32_16x16x32_bf16 v[6:9], v[98:101], v[18:21], v[86:89]
	v_mfma_f32_16x16x32_bf16 v[64:67], v[102:105], v[28:31], v[6:9]
	v_mfma_f32_16x16x32_bf16 v[6:9], v[226:229], v[18:21], v[82:85]
	v_mfma_f32_16x16x32_bf16 v[126:129], v[198:201], v[28:31], v[6:9]
	v_mfma_f32_16x16x32_bf16 v[6:9], v[98:101], v[188:191], v[78:81]
	v_mfma_f32_16x16x32_bf16 v[134:137], v[102:105], v[14:17], v[46:49]
	v_mfma_f32_16x16x32_bf16 v[46:49], v[102:105], v[192:195], v[6:9]
	v_mfma_f32_16x16x32_bf16 v[6:9], v[226:229], v[188:191], v[152:155]
	v_mfma_f32_16x16x32_bf16 v[122:125], v[198:201], v[192:195], v[6:9]
	v_mfma_f32_16x16x32_bf16 v[6:9], v[98:101], v[242:245], v[156:159]
	v_mfma_f32_16x16x32_bf16 v[16:19], v[102:105], v[246:249], v[6:9]
	v_mfma_f32_16x16x32_bf16 v[6:9], v[226:229], v[242:245], v[160:163]
	v_mfma_f32_16x16x32_bf16 v[118:121], v[198:201], v[246:249], v[6:9]
	s_setprio 0
	s_barrier
	ds_read_b128 v[76:79], v142 offset:49152
	ds_read_b128 v[86:89], v142 offset:50176
	ds_read_b128 v[106:109], v142 offset:51200
	ds_read_b128 v[110:113], v142 offset:52224
	ds_read_b128 v[158:161], v142 offset:53248
	ds_read_b128 v[188:191], v142 offset:54272
	ds_read_b128 v[192:195], v142 offset:55296
	ds_read_b128 v[242:245], v142 offset:56320
	s_barrier
	s_waitcnt lgkmcnt(0)
	s_setprio 1
	s_waitcnt lgkmcnt(0)
	v_mfma_f32_16x16x32_bf16 v[6:9], v[2:5], v[76:79], v[202:205]
	v_mfma_f32_16x16x32_bf16 v[154:157], v[72:75], v[86:89], v[6:9]
	v_mfma_f32_16x16x32_bf16 v[6:9], v[180:183], v[76:79], v[206:209]
	v_mfma_f32_16x16x32_bf16 v[30:33], v[184:187], v[86:89], v[6:9]
	v_mfma_f32_16x16x32_bf16 v[6:9], v[2:5], v[106:109], v[50:53]
	v_mfma_f32_16x16x32_bf16 v[92:95], v[72:75], v[110:113], v[6:9]
	v_mfma_f32_16x16x32_bf16 v[6:9], v[180:183], v[106:109], v[210:213]
	v_mfma_f32_16x16x32_bf16 v[20:23], v[184:187], v[110:113], v[6:9]
	v_mfma_f32_16x16x32_bf16 v[6:9], v[2:5], v[158:161], v[214:217]
	v_mfma_f32_16x16x32_bf16 v[2:5], v[2:5], v[192:195], v[138:141]
	v_mfma_f32_16x16x32_bf16 v[82:85], v[72:75], v[188:191], v[6:9]
	v_mfma_f32_16x16x32_bf16 v[6:9], v[180:183], v[158:161], v[218:221]
	v_mfma_f32_16x16x32_bf16 v[72:75], v[72:75], v[242:245], v[2:5]
	v_mfma_f32_16x16x32_bf16 v[2:5], v[180:183], v[192:195], v[144:147]
	v_mfma_f32_16x16x32_bf16 v[6:9], v[184:187], v[188:191], v[6:9]
	v_mfma_f32_16x16x32_bf16 v[2:5], v[184:187], v[242:245], v[2:5]
	s_setprio 0
	s_setprio 1
	v_mfma_f32_16x16x32_bf16 v[50:53], v[98:101], v[76:79], v[148:151]
	v_mfma_f32_16x16x32_bf16 v[150:153], v[102:105], v[86:89], v[50:53]
	v_mfma_f32_16x16x32_bf16 v[50:53], v[226:229], v[76:79], v[230:233]
	v_mfma_f32_16x16x32_bf16 v[114:117], v[198:201], v[86:89], v[50:53]
	v_mfma_f32_16x16x32_bf16 v[50:53], v[98:101], v[106:109], v[234:237]
	v_mfma_f32_16x16x32_bf16 v[146:149], v[102:105], v[110:113], v[50:53]
	v_mfma_f32_16x16x32_bf16 v[50:53], v[226:229], v[106:109], v[164:167]
	v_mfma_f32_16x16x32_bf16 v[110:113], v[198:201], v[110:113], v[50:53]
	v_mfma_f32_16x16x32_bf16 v[50:53], v[98:101], v[158:161], v[238:241]
	v_mfma_f32_16x16x32_bf16 v[142:145], v[102:105], v[188:191], v[50:53]
	v_mfma_f32_16x16x32_bf16 v[50:53], v[226:229], v[158:161], v[168:171]
	v_mfma_f32_16x16x32_bf16 v[106:109], v[198:201], v[188:191], v[50:53]
	v_mfma_f32_16x16x32_bf16 v[50:53], v[98:101], v[192:195], v[172:175]
	v_mfma_f32_16x16x32_bf16 v[138:141], v[102:105], v[242:245], v[50:53]
	v_mfma_f32_16x16x32_bf16 v[50:53], v[226:229], v[192:195], v[176:179]
	v_mfma_f32_16x16x32_bf16 v[102:105], v[198:201], v[242:245], v[50:53]
	s_setprio 0
	s_cmpk_lt_u32 s1, 0x100
	s_barrier
	s_cbranch_scc0 .LBB0_199
	s_barrier
